# attention: QK^T K-fragment LDS reads double-buffered (issued one step ahead, counted lgkmcnt), PV group waits counted per MFMA
# baseline (speedup 1.0000x reference)
; __device__ __forceinline__ void finishSM(f32x16& p0, f32x16& p1, float alpha, float& l_reg, bf16x8& pa0, bf16x8& pa1, bf16x8& pa2, bf16x8& pa3) {
;   for (int r = 0; r < 16; ++r) p1[r] = __builtin_amdgcn_exp2f(p1[r]);
;   float ps = 0; for (int r = 0; r < 16; ++r) ps += p0[r]; for (int r = 0; r < 16; ++r) ps += p1[r];
;   { auto rr = __builtin_amdgcn_permlane32_swap(__float_as_uint(ps), __float_as_uint(ps), false, false);
;     ps = __uint_as_float(rr[0]) + __uint_as_float(rr[1]); }
;   l_reg = l_reg * alpha + ps;
;     ...
;   PK4(p0, 0, pa0); PK4(p0, 8, pa1); PK4(p1, 0, pa2); PK4(p1, 8, pa3);
; template <int qh> __device__ __forceinline__ void qkt(f32x16& p0, f32x16& p1, const bf16_t* Ks, const bf16x8* qr, int r32, int hi) {
;   p0 = f32x16{}; p1 = f32x16{};
;   if constexpr (qh != 2) { QKT_STEP(0); QKT_STEP(1); QKT_STEP(2); QKT_STEP(3); }
;   if constexpr (qh != 1) { QKT_STEP(4); QKT_STEP(5); QKT_STEP(6); QKT_STEP(7); }
.LBB0_100:
	s_add_i32 s8, s73, 0xffff8000
	s_and_b32 s36, s8, 0x18000
	s_add_i32 s8, s36, 0
	v_add_u32_e32 v68, s8, v175
	ds_read_b128 v[64:67], v68
	ds_read_b128 v[68:71], v68 offset:8192
	v_add_u32_e32 v198, s8, v176
	ds_read_b128 v[218:221], v198
	ds_read_b128 v[222:225], v198 offset:8192
	s_waitcnt lgkmcnt(0)
	v_mfma_f32_32x32x16_bf16 v[80:95], v[64:67], v[124:127], 0
	v_exp_f32_e32 v226, v156
	v_add_f32_e32 v156, 0, v209
	v_add_f32_e32 v156, v210, v156
	v_add_f32_e32 v156, v211, v156
	v_add_f32_e32 v156, v213, v156
	v_add_f32_e32 v156, v215, v156
	v_add_f32_e32 v156, v216, v156
	v_mfma_f32_32x32x16_bf16 v[64:79], v[68:71], v[124:127], 0
	v_add_f32_e32 v156, v212, v156
	v_add_f32_e32 v156, v214, v156
	v_add_f32_e32 v156, v201, v156
	v_add_f32_e32 v156, v203, v156
	v_add_f32_e32 v156, v205, v156
	v_add_f32_e32 v156, v207, v156
	v_exp_f32_e32 v170, v170
	v_mfma_f32_32x32x16_bf16 v[80:95], v[218:221], v[120:123], v[80:95]
	v_add_f32_e32 v156, v202, v156
	v_exp_f32_e32 v171, v171
	v_add_f32_e32 v156, v204, v156
	v_exp_f32_e32 v168, v168
	v_add_f32_e32 v156, v206, v156
	v_exp_f32_e32 v169, v169
	v_add_f32_e32 v156, v208, v156
	v_mfma_f32_32x32x16_bf16 v[64:79], v[222:225], v[120:123], v[64:79]
	v_add_u32_e32 v198, s8, v177
	ds_read_b128 v[218:221], v198
	ds_read_b128 v[222:225], v198 offset:8192
	v_add_u32_e32 v236, s8, v178
	ds_read_b128 v[228:231], v236
	ds_read_b128 v[232:235], v236 offset:8192
	v_add_f32_e32 v156, v170, v156
	v_exp_f32_e32 v217, v167
	v_add_f32_e32 v156, v171, v156
	v_add_f32_e32 v156, v168, v156
	v_add_f32_e32 v156, v169, v156
	s_waitcnt lgkmcnt(2)
	v_mfma_f32_32x32x16_bf16 v[80:95], v[218:221], v[116:119], v[80:95]
	v_exp_f32_e32 v227, v157
	v_cvt_pk_bf16_f32 v167, v168, v169
	v_mfma_f32_32x32x16_bf16 v[64:79], v[222:225], v[116:119], v[64:79]
	v_add_u32_e32 v198, s8, v179
	ds_read_b128 v[218:221], v198
	ds_read_b128 v[222:225], v198 offset:8192
	s_waitcnt lgkmcnt(2)
	v_mfma_f32_32x32x16_bf16 v[80:95], v[228:231], v[112:115], v[80:95]
	v_mfma_f32_32x32x16_bf16 v[64:79], v[232:235], v[112:115], v[64:79]
	v_add_u32_e32 v236, s8, v180
	ds_read_b128 v[228:231], v236
	ds_read_b128 v[232:235], v236 offset:8192
	s_waitcnt lgkmcnt(2)
	v_mfma_f32_32x32x16_bf16 v[80:95], v[218:221], v[108:111], v[80:95]
	v_mfma_f32_32x32x16_bf16 v[64:79], v[222:225], v[108:111], v[64:79]
	v_add_u32_e32 v198, s8, v181
	ds_read_b128 v[218:221], v198
	ds_read_b128 v[222:225], v198 offset:8192
	s_waitcnt lgkmcnt(2)
	v_mfma_f32_32x32x16_bf16 v[80:95], v[228:231], v[104:107], v[80:95]
	v_mfma_f32_32x32x16_bf16 v[64:79], v[232:235], v[104:107], v[64:79]
	v_add_u32_e32 v236, s8, v182
	ds_read_b128 v[228:231], v236
	ds_read_b128 v[232:235], v236 offset:8192
	s_waitcnt lgkmcnt(2)
	v_mfma_f32_32x32x16_bf16 v[80:95], v[218:221], v[100:103], v[80:95]
	v_mfma_f32_32x32x16_bf16 v[64:79], v[222:225], v[100:103], v[64:79]
	v_exp_f32_e32 v198, v166
	v_cvt_pk_bf16_f32 v166, v170, v171
	v_add_f32_e32 v156, v198, v156
	v_add_f32_e32 v156, v217, v156
	s_waitcnt lgkmcnt(0)
	v_mfma_f32_32x32x16_bf16 v[80:95], v[228:231], v[96:99], v[80:95]
	v_exp_f32_e32 v218, v164
	v_exp_f32_e32 v219, v165
	v_exp_f32_e32 v220, v162
	v_exp_f32_e32 v221, v163
	v_add_f32_e32 v156, v218, v156
	v_add_f32_e32 v156, v219, v156
	v_add_f32_e32 v156, v220, v156
	v_mfma_f32_32x32x16_bf16 v[64:79], v[232:235], v[96:99], v[64:79]
	v_exp_f32_e32 v222, v160
	v_exp_f32_e32 v223, v161
	v_exp_f32_e32 v224, v158
	v_exp_f32_e32 v225, v159
	v_add_f32_e32 v156, v221, v156
	v_add_f32_e32 v156, v222, v156
	v_add_f32_e32 v156, v223, v156
	v_add_f32_e32 v156, v224, v156
	v_add_f32_e32 v156, v225, v156
	v_add_f32_e32 v156, v226, v156
	v_add_f32_e32 v156, v227, v156
	v_mov_b32_e32 v157, v156
	v_cvt_pk_bf16_f32 v158, v209, v210
	v_cvt_pk_bf16_f32 v160, v215, v216
	v_permlane32_swap_b32_e32 v156, v157
	v_cvt_pk_bf16_f32 v159, v211, v213
	v_cvt_pk_bf16_f32 v161, v212, v214
	v_permlane32_swap_b32_e32 v158, v160
	v_cvt_pk_bf16_f32 v162, v201, v203
	v_cvt_pk_bf16_f32 v163, v205, v207
	v_cvt_pk_bf16_f32 v164, v202, v204
	v_cvt_pk_bf16_f32 v165, v206, v208
	v_cvt_pk_bf16_f32 v168, v198, v217
	v_cvt_pk_bf16_f32 v169, v218, v219
	v_cvt_pk_bf16_f32 v202, v220, v221
	v_cvt_pk_bf16_f32 v203, v222, v223
	v_cvt_pk_bf16_f32 v204, v224, v225
	v_cvt_pk_bf16_f32 v205, v226, v227
	v_permlane32_swap_b32_e32 v159, v161
	v_permlane32_swap_b32_e32 v162, v164
	v_permlane32_swap_b32_e32 v163, v165
	v_permlane32_swap_b32_e32 v166, v168
	v_permlane32_swap_b32_e32 v167, v169
	v_permlane32_swap_b32_e32 v202, v204
	v_permlane32_swap_b32_e32 v203, v205
	s_add_i32 s15, s73, 0x10000
	s_and_b32 s38, s15, 0x18000
	v_add_u32_e32 v170, s38, v173
	ds_read_b64_tr_b16 v[206:207], v170 offset:0
	ds_read_b64_tr_b16 v[208:209], v170 offset:0x800
	ds_read_b64_tr_b16 v[210:211], v170 offset:0x1000
	ds_read_b64_tr_b16 v[212:213], v170 offset:0x1800
	ds_read_b64_tr_b16 v[214:215], v170 offset:0x2000
	ds_read_b64_tr_b16 v[216:217], v170 offset:0x2800
	ds_read_b64_tr_b16 v[218:219], v170 offset:0x3000
	ds_read_b64_tr_b16 v[220:221], v170 offset:0x3800
	s_waitcnt lgkmcnt(6)
; #define SBAR() __builtin_amdgcn_sched_barrier(0)
; __device__ __forceinline__ void partialSM(f32x16& p0, f32x16& p1, float& m_reg, float& mn, float& alpha, float C, float thr) {
;   float pmax = p0[0]; for (int r = 1; r < 16; ++r) pmax = fmaxf(pmax, p0[r]); for (int r = 0; r < 16; ++r) pmax = fmaxf(pmax, p1[r]);
;   { auto rr = __builtin_amdgcn_permlane32_swap(__float_as_uint(pmax), __float_as_uint(pmax), false, false);
;     pmax = fmaxf(__uint_as_float(rr[0]), __uint_as_float(rr[1])); }
;   if (__builtin_expect(__all(pmax - m_reg <= thr), 1)) { mn = m_reg; alpha = 1.f; }
; template <int D0> __device__ __forceinline__ void pv_one(f32x16& od, int vb, bf16x8 pa0, bf16x8 pa1, bf16x8 pa2, bf16x8 pa3) {
;   const s16x4 l0 = tr_read<v_rd_off(D0, 0, 0)>(vb), h0 = tr_read<v_rd_off(D0, 0, 1)>(vb), l1 = tr_read<v_rd_off(D0, 1, 0)>(vb), h1 = tr_read<v_rd_off(D0, 1, 1)>(vb);
;   const s16x4 l2 = tr_read<v_rd_off(D0, 2, 0)>(vb), h2 = tr_read<v_rd_off(D0, 2, 1)>(vb), l3 = tr_read<v_rd_off(D0, 3, 0)>(vb), h3 = tr_read<v_rd_off(D0, 3, 1)>(vb);
;   asm volatile("s_waitcnt lgkmcnt(0)" ::: "memory"); SBAR();
;     ...
;   od = __builtin_amdgcn_mfma_f32_32x32x16_bf16(pa0, PK(l0, h0), od, 0, 0, 0);
;   od = __builtin_amdgcn_mfma_f32_32x32x16_bf16(pa1, PK(l1, h1), od, 0, 0, 0);
;   od = __builtin_amdgcn_mfma_f32_32x32x16_bf16(pa2, PK(l2, h2), od, 0, 0, 0);
;   od = __builtin_amdgcn_mfma_f32_32x32x16_bf16(pa3, PK(l3, h3), od, 0, 0, 0);
;     ...
; }
; __device__ __forceinline__ void pv_d0(f32x16* o, int vb, bf16x8 pa0, bf16x8 pa1, bf16x8 pa2, bf16x8 pa3) {
;   pv_one<0>(o[0], vb, pa0, pa1, pa2, pa3); pv_one<1>(o[1], vb, pa0, pa1, pa2, pa3); pv_one<2>(o[2], vb, pa0, pa1, pa2, pa3); pv_one<3>(o[3], vb, pa0, pa1, pa2, pa3);
	s_nop 0
	v_mfma_f32_32x32x16_bf16 v[0:15], v[158:161], v[206:209], v[0:15]
	ds_read_b64_tr_b16 v[206:207], v170 offset:0x200
	ds_read_b64_tr_b16 v[208:209], v170 offset:0xa00
	s_waitcnt lgkmcnt(6)
	v_mfma_f32_32x32x16_bf16 v[0:15], v[162:165], v[210:213], v[0:15]
	ds_read_b64_tr_b16 v[210:211], v170 offset:0x1200
	ds_read_b64_tr_b16 v[212:213], v170 offset:0x1a00
	s_waitcnt lgkmcnt(6)
	v_mfma_f32_32x32x16_bf16 v[0:15], v[166:169], v[214:217], v[0:15]
	ds_read_b64_tr_b16 v[214:215], v170 offset:0x2200
	ds_read_b64_tr_b16 v[216:217], v170 offset:0x2a00
	s_waitcnt lgkmcnt(6)
	v_mfma_f32_32x32x16_bf16 v[0:15], v[202:205], v[218:221], v[0:15]
	ds_read_b64_tr_b16 v[218:219], v170 offset:0x3200
	ds_read_b64_tr_b16 v[220:221], v170 offset:0x3a00
	s_waitcnt lgkmcnt(6)
	v_mfma_f32_32x32x16_bf16 v[48:63], v[158:161], v[206:209], v[48:63]
	ds_read_b64_tr_b16 v[206:207], v170 offset:0x400
	ds_read_b64_tr_b16 v[208:209], v170 offset:0xc00
	s_waitcnt lgkmcnt(6)
	v_mfma_f32_32x32x16_bf16 v[48:63], v[162:165], v[210:213], v[48:63]
	ds_read_b64_tr_b16 v[210:211], v170 offset:0x1400
	ds_read_b64_tr_b16 v[212:213], v170 offset:0x1c00
	s_waitcnt lgkmcnt(6)
	v_mfma_f32_32x32x16_bf16 v[48:63], v[166:169], v[214:217], v[48:63]
	ds_read_b64_tr_b16 v[214:215], v170 offset:0x2400
	ds_read_b64_tr_b16 v[216:217], v170 offset:0x2c00
	s_waitcnt lgkmcnt(6)
	v_mfma_f32_32x32x16_bf16 v[48:63], v[202:205], v[218:221], v[48:63]
	ds_read_b64_tr_b16 v[218:219], v170 offset:0x3400
	ds_read_b64_tr_b16 v[220:221], v170 offset:0x3c00
	s_waitcnt lgkmcnt(6)
	v_mfma_f32_32x32x16_bf16 v[32:47], v[158:161], v[206:209], v[32:47]
	ds_read_b64_tr_b16 v[206:207], v170 offset:0x600
	ds_read_b64_tr_b16 v[208:209], v170 offset:0xe00
	s_waitcnt lgkmcnt(6)
	v_mfma_f32_32x32x16_bf16 v[32:47], v[162:165], v[210:213], v[32:47]
	ds_read_b64_tr_b16 v[210:211], v170 offset:0x1600
	ds_read_b64_tr_b16 v[212:213], v170 offset:0x1e00
	s_waitcnt lgkmcnt(6)
	v_mfma_f32_32x32x16_bf16 v[32:47], v[166:169], v[214:217], v[32:47]
	ds_read_b64_tr_b16 v[214:215], v170 offset:0x2600
	ds_read_b64_tr_b16 v[216:217], v170 offset:0x2e00
	s_waitcnt lgkmcnt(6)
	v_mfma_f32_32x32x16_bf16 v[32:47], v[202:205], v[218:221], v[32:47]
	ds_read_b64_tr_b16 v[218:219], v170 offset:0x3600
	ds_read_b64_tr_b16 v[220:221], v170 offset:0x3e00
	s_waitcnt lgkmcnt(6)
	v_mfma_f32_32x32x16_bf16 v[16:31], v[158:161], v[206:209], v[16:31]
	v_max_f32_e32 v158, v81, v81
	v_max_f32_e32 v159, v80, v80
	v_max_f32_e32 v158, v159, v158
	v_max3_f32 v158, v158, v82, v83
	v_max3_f32 v158, v158, v84, v85
	v_max3_f32 v158, v158, v86, v87
	v_max3_f32 v158, v158, v88, v89
	s_waitcnt lgkmcnt(4)
	v_mfma_f32_32x32x16_bf16 v[16:31], v[162:165], v[210:213], v[16:31]
	v_max3_f32 v158, v158, v90, v91
	v_max3_f32 v158, v158, v92, v93
	v_max3_f32 v158, v158, v94, v95
	v_max3_f32 v158, v158, v64, v65
	v_max3_f32 v158, v158, v66, v67
	v_max3_f32 v158, v158, v68, v69
	v_max3_f32 v158, v158, v70, v71
	s_waitcnt lgkmcnt(2)
	v_mfma_f32_32x32x16_bf16 v[16:31], v[166:169], v[214:217], v[16:31]
	v_max3_f32 v158, v158, v72, v73
	v_max3_f32 v158, v158, v74, v75
	v_max3_f32 v158, v158, v76, v77
	v_max3_f32 v158, v158, v78, v79
	v_mov_b32_e32 v159, v158
	s_nop 1
	v_permlane32_swap_b32_e32 v158, v159
	s_waitcnt lgkmcnt(0)
	v_mfma_f32_32x32x16_bf16 v[16:31], v[202:205], v[218:221], v[16:31]
	v_max_f32_e32 v159, v159, v159
	v_max_f32_e32 v158, v158, v158
	v_max_f32_e32 v158, v158, v159
	v_sub_f32_e32 v159, v158, v199
	v_cmp_ge_f32_e64 s[8:9], s40, v159
	s_mov_b64 s[24:25], -1
	s_and_b64 vcc, exec, s[22:23]
	s_cbranch_vccz .LBB0_102
	s_waitcnt vmcnt(0)
	s_mov_b64 s[24:25], 0

; __device__ __forceinline__ void partialSM(f32x16& p0, f32x16& p1, float& m_reg, float& mn, float& alpha, float C, float thr) {
;     ...
;   else { mn = fmaxf(m_reg, pmax); alpha = __builtin_amdgcn_exp2f((m_reg - mn) * C); m_reg = mn; }
;   float mnC = -mn * C;
;   for (int r = 0; r < 16; ++r) p0[r] = fmaf(p0[r], C, mnC); for (int r = 0; r < 16; ++r) p1[r] = fmaf(p1[r], C, mnC);
;   for (int r = 0; r < 16; ++r) p0[r] = __builtin_amdgcn_exp2f(p0[r]);
; template <int qh> __device__ __forceinline__ void qkt(f32x16& p0, f32x16& p1, const bf16_t* Ks, const bf16x8* qr, int r32, int hi) {
;   p0 = f32x16{}; p1 = f32x16{};
;   if constexpr (qh != 2) { QKT_STEP(0); QKT_STEP(1); QKT_STEP(2); QKT_STEP(3); }
;   if constexpr (qh != 1) { QKT_STEP(4); QKT_STEP(5); QKT_STEP(6); QKT_STEP(7); }
.LBB0_110:
	v_cndmask_b32_e64 v143, v159, v199, s[8:9]
	v_mul_f32_e32 v142, 0xbe0293ee, v143
	v_fmamk_f32 v80, v80, 0x3e0293ee, v142
	v_fmamk_f32 v81, v81, 0x3e0293ee, v142
	v_fmamk_f32 v82, v82, 0x3e0293ee, v142
	v_fmamk_f32 v83, v83, 0x3e0293ee, v142
	v_fmamk_f32 v84, v84, 0x3e0293ee, v142
	v_fmamk_f32 v85, v85, 0x3e0293ee, v142
	v_fmamk_f32 v86, v86, 0x3e0293ee, v142
	v_fmamk_f32 v87, v87, 0x3e0293ee, v142
	v_fmamk_f32 v88, v88, 0x3e0293ee, v142
	v_fmamk_f32 v89, v89, 0x3e0293ee, v142
	v_fmamk_f32 v90, v90, 0x3e0293ee, v142
	v_fmamk_f32 v91, v91, 0x3e0293ee, v142
	v_fmamk_f32 v92, v92, 0x3e0293ee, v142
	v_fmamk_f32 v93, v93, 0x3e0293ee, v142
	v_fmamk_f32 v94, v94, 0x3e0293ee, v142
	v_fmamk_f32 v95, v95, 0x3e0293ee, v142
	v_fmamk_f32 v154, v64, 0x3e0293ee, v142
	v_fmamk_f32 v155, v65, 0x3e0293ee, v142
	v_fmamk_f32 v159, v66, 0x3e0293ee, v142
	v_fmamk_f32 v164, v67, 0x3e0293ee, v142
	v_fmamk_f32 v165, v68, 0x3e0293ee, v142
	v_fmamk_f32 v166, v69, 0x3e0293ee, v142
	v_fmamk_f32 v167, v70, 0x3e0293ee, v142
	v_fmamk_f32 v168, v71, 0x3e0293ee, v142
	v_fmamk_f32 v169, v72, 0x3e0293ee, v142
	v_fmamk_f32 v170, v73, 0x3e0293ee, v142
	v_fmamk_f32 v171, v74, 0x3e0293ee, v142
	v_fmamk_f32 v198, v75, 0x3e0293ee, v142
	v_fmamk_f32 v199, v76, 0x3e0293ee, v142
	v_fmamk_f32 v217, v77, 0x3e0293ee, v142
	v_fmamk_f32 v218, v78, 0x3e0293ee, v142
	v_fmac_f32_e32 v142, 0x3e0293ee, v79
	v_exp_f32_e32 v201, v80
	v_exp_f32_e32 v202, v81
	v_exp_f32_e32 v203, v82
	v_exp_f32_e32 v204, v83
	v_exp_f32_e32 v205, v84
	v_exp_f32_e32 v206, v85
	v_exp_f32_e32 v207, v86
	v_exp_f32_e32 v208, v87
	v_exp_f32_e32 v209, v88
	v_exp_f32_e32 v210, v89
	v_exp_f32_e32 v211, v90
	v_exp_f32_e32 v212, v91
	v_exp_f32_e32 v213, v92
	v_exp_f32_e32 v214, v93
	v_exp_f32_e32 v215, v94
	v_exp_f32_e32 v216, v95
	s_and_b32 s8, s73, 0x18000
	s_add_i32 s8, s8, 0
	v_add_u32_e32 v68, s8, v175
	ds_read_b128 v[64:67], v68
	ds_read_b128 v[68:71], v68 offset:8192
	v_add_u32_e32 v160, s8, v176
	ds_read_b128 v[150:153], v160
	ds_read_b128 v[160:163], v160 offset:8192
	v_exp_f32_e32 v219, v154
	s_waitcnt lgkmcnt(0)
	v_mfma_f32_32x32x16_bf16 v[80:95], v[64:67], v[124:127], 0
	v_exp_f32_e32 v220, v155
	v_exp_f32_e32 v159, v159
	v_exp_f32_e32 v221, v164
	v_exp_f32_e32 v222, v165
	v_exp_f32_e32 v166, v166
	v_exp_f32_e32 v167, v167
	v_exp_f32_e32 v168, v168
	v_mfma_f32_32x32x16_bf16 v[64:79], v[68:71], v[124:127], 0
	v_exp_f32_e32 v169, v169
	v_exp_f32_e32 v170, v170
	v_exp_f32_e32 v171, v171
	v_exp_f32_e32 v198, v198
	v_exp_f32_e32 v199, v199
	v_exp_f32_e32 v217, v217
	v_exp_f32_e32 v218, v218
	v_mfma_f32_32x32x16_bf16 v[80:95], v[150:153], v[120:123], v[80:95]
	v_exp_f32_e32 v142, v142
	v_cvt_pk_bf16_f32 v154, v205, v206
	v_cvt_pk_bf16_f32 v155, v207, v208
	v_cvt_pk_bf16_f32 v164, v219, v220
	v_cvt_pk_bf16_f32 v165, v159, v221
	v_mfma_f32_32x32x16_bf16 v[64:79], v[160:163], v[120:123], v[64:79]
	v_add_u32_e32 v160, s8, v177
	ds_read_b128 v[150:153], v160
	ds_read_b128 v[160:163], v160 offset:8192
	v_add_u32_e32 v236, s8, v178
	ds_read_b128 v[228:231], v236
	ds_read_b128 v[232:235], v236 offset:8192
	s_waitcnt lgkmcnt(2)
	v_mfma_f32_32x32x16_bf16 v[80:95], v[150:153], v[116:119], v[80:95]
	v_mfma_f32_32x32x16_bf16 v[64:79], v[160:163], v[116:119], v[64:79]
	v_add_u32_e32 v160, s8, v179
	ds_read_b128 v[150:153], v160
	ds_read_b128 v[160:163], v160 offset:8192
	s_waitcnt lgkmcnt(2)
	v_mfma_f32_32x32x16_bf16 v[80:95], v[228:231], v[112:115], v[80:95]
	v_mfma_f32_32x32x16_bf16 v[64:79], v[232:235], v[112:115], v[64:79]
	v_add_u32_e32 v236, s8, v180
	ds_read_b128 v[228:231], v236
	ds_read_b128 v[232:235], v236 offset:8192
	s_waitcnt lgkmcnt(2)
	v_mfma_f32_32x32x16_bf16 v[80:95], v[150:153], v[108:111], v[80:95]
	v_mfma_f32_32x32x16_bf16 v[64:79], v[160:163], v[108:111], v[64:79]
	v_add_u32_e32 v160, s8, v181
	ds_read_b128 v[150:153], v160
	ds_read_b128 v[160:163], v160 offset:8192
	s_waitcnt lgkmcnt(2)
	v_mfma_f32_32x32x16_bf16 v[80:95], v[228:231], v[104:107], v[80:95]
	v_mfma_f32_32x32x16_bf16 v[64:79], v[232:235], v[104:107], v[64:79]
	v_add_u32_e32 v236, s8, v182
	ds_read_b128 v[228:231], v236
	ds_read_b128 v[232:235], v236 offset:8192
	s_waitcnt lgkmcnt(2)
	v_mfma_f32_32x32x16_bf16 v[80:95], v[150:153], v[100:103], v[80:95]
	v_mfma_f32_32x32x16_bf16 v[64:79], v[160:163], v[100:103], v[64:79]
	s_waitcnt lgkmcnt(0)
; #define SBAR() __builtin_amdgcn_sched_barrier(0)
; __device__ __forceinline__ void finishSM(f32x16& p0, f32x16& p1, float alpha, float& l_reg, bf16x8& pa0, bf16x8& pa1, bf16x8& pa2, bf16x8& pa3) {
;   for (int r = 0; r < 16; ++r) p1[r] = __builtin_amdgcn_exp2f(p1[r]);
;   float ps = 0; for (int r = 0; r < 16; ++r) ps += p0[r]; for (int r = 0; r < 16; ++r) ps += p1[r];
;   { auto rr = __builtin_amdgcn_permlane32_swap(__float_as_uint(ps), __float_as_uint(ps), false, false);
;     ps = __uint_as_float(rr[0]) + __uint_as_float(rr[1]); }
;   l_reg = l_reg * alpha + ps;
;     ...
;   PK4(p0, 0, pa0); PK4(p0, 8, pa1); PK4(p1, 0, pa2); PK4(p1, 8, pa3);
;     ...
; }
; template <int qh> __device__ __forceinline__ void qkt(f32x16& p0, f32x16& p1, const bf16_t* Ks, const bf16x8* qr, int r32, int hi) {
;   p0 = f32x16{}; p1 = f32x16{};
;   if constexpr (qh != 2) { QKT_STEP(0); QKT_STEP(1); QKT_STEP(2); QKT_STEP(3); }
;   if constexpr (qh != 1) { QKT_STEP(4); QKT_STEP(5); QKT_STEP(6); QKT_STEP(7); }
; }
; __device__ __forceinline__ int v_st(int k, int c) { const int kk = (k & ~0xC) | ((k & 4) << 1) | ((k & 8) >> 1); return ((kk >> 3) * 4 + (c >> 5)) * 512 + ((kk & 7) * 32 + (c & 31)) * 2; }
; __device__ __forceinline__ int v_rd_base(int lane) { return ((lane & 3) << 3) | (((lane >> 2) & 3) << 6) | (((lane >> 4) & 1) << 5) | (((lane >> 5) & 1) << 8); }
; template <int OFF> __device__ __forceinline__ s16x4 tr_read(int vb) {
;   s16x4 r; asm volatile("ds_read_b64_tr_b16 %0, %1 offset:%2" : "=&v"(r) : "v"(vb), "i"(OFF) : "memory"); return r;
; }
; template <int D0> __device__ __forceinline__ void pv_one(f32x16& od, int vb, bf16x8 pa0, bf16x8 pa1, bf16x8 pa2, bf16x8 pa3) {
;   const s16x4 l0 = tr_read<v_rd_off(D0, 0, 0)>(vb), h0 = tr_read<v_rd_off(D0, 0, 1)>(vb), l1 = tr_read<v_rd_off(D0, 1, 0)>(vb), h1 = tr_read<v_rd_off(D0, 1, 1)>(vb);
;   const s16x4 l2 = tr_read<v_rd_off(D0, 2, 0)>(vb), h2 = tr_read<v_rd_off(D0, 2, 1)>(vb), l3 = tr_read<v_rd_off(D0, 3, 0)>(vb), h3 = tr_read<v_rd_off(D0, 3, 1)>(vb);
;   asm volatile("s_waitcnt lgkmcnt(0)" ::: "memory"); SBAR();
;     ...
;   od = __builtin_amdgcn_mfma_f32_32x32x16_bf16(pa0, PK(l0, h0), od, 0, 0, 0);
;   od = __builtin_amdgcn_mfma_f32_32x32x16_bf16(pa1, PK(l1, h1), od, 0, 0, 0);
;   od = __builtin_amdgcn_mfma_f32_32x32x16_bf16(pa2, PK(l2, h2), od, 0, 0, 0);
;   od = __builtin_amdgcn_mfma_f32_32x32x16_bf16(pa3, PK(l3, h3), od, 0, 0, 0);
;     ...
; }
	v_mfma_f32_32x32x16_bf16 v[80:95], v[228:231], v[96:99], v[80:95]
	v_add_f32_e32 v150, 0, v201
	v_add_f32_e32 v150, v202, v150
	v_add_f32_e32 v150, v203, v150
	v_add_f32_e32 v150, v204, v150
	v_add_f32_e32 v150, v205, v150
	v_add_f32_e32 v150, v206, v150
	v_add_f32_e32 v150, v207, v150
	v_add_f32_e32 v150, v208, v150
	v_add_f32_e32 v150, v209, v150
	v_add_f32_e32 v150, v210, v150
	v_add_f32_e32 v150, v211, v150
	v_add_f32_e32 v150, v212, v150
	v_add_f32_e32 v150, v213, v150
	v_add_f32_e32 v150, v214, v150
	v_add_f32_e32 v150, v215, v150
	v_add_f32_e32 v150, v216, v150
	v_add_f32_e32 v150, v219, v150
	v_add_f32_e32 v150, v220, v150
	v_add_f32_e32 v150, v159, v150
	v_add_f32_e32 v150, v221, v150
	v_add_f32_e32 v150, v222, v150
	v_add_f32_e32 v150, v166, v150
	v_add_f32_e32 v150, v167, v150
	v_add_f32_e32 v150, v168, v150
	v_add_f32_e32 v150, v169, v150
	v_add_f32_e32 v150, v170, v150
	v_mfma_f32_32x32x16_bf16 v[64:79], v[232:235], v[96:99], v[64:79]
	v_add_f32_e32 v150, v171, v150
	v_add_f32_e32 v150, v198, v150
	v_add_f32_e32 v150, v199, v150
	v_add_f32_e32 v150, v217, v150
	v_add_f32_e32 v150, v218, v150
	v_add_f32_e32 v150, v142, v150
	v_mov_b32_e32 v151, v150
	s_nop 1
	v_permlane32_swap_b32_e32 v150, v151
	v_cvt_pk_bf16_f32 v152, v201, v202
	v_cvt_pk_bf16_f32 v153, v203, v204
	v_cvt_pk_bf16_f32 v160, v209, v210
	v_cvt_pk_bf16_f32 v161, v211, v212
	v_cvt_pk_bf16_f32 v162, v213, v214
	v_cvt_pk_bf16_f32 v163, v215, v216
	v_cvt_pk_bf16_f32 v166, v222, v166
	v_cvt_pk_bf16_f32 v167, v167, v168
	v_cvt_pk_bf16_f32 v168, v169, v170
	v_cvt_pk_bf16_f32 v169, v171, v198
	v_cvt_pk_bf16_f32 v170, v199, v217
	v_cvt_pk_bf16_f32 v171, v218, v142
	v_permlane32_swap_b32_e32 v152, v154
	v_permlane32_swap_b32_e32 v153, v155
	v_permlane32_swap_b32_e32 v160, v162
	v_permlane32_swap_b32_e32 v161, v163
	v_permlane32_swap_b32_e32 v164, v166
	v_permlane32_swap_b32_e32 v165, v167
	v_permlane32_swap_b32_e32 v168, v170
	v_permlane32_swap_b32_e32 v169, v171
	v_add_u32_e32 v142, s36, v173
	ds_read_b64_tr_b16 v[202:203], v142 offset:0
	ds_read_b64_tr_b16 v[204:205], v142 offset:0x800
	ds_read_b64_tr_b16 v[206:207], v142 offset:0x1000
	ds_read_b64_tr_b16 v[208:209], v142 offset:0x1800
	ds_read_b64_tr_b16 v[210:211], v142 offset:0x2000
	ds_read_b64_tr_b16 v[212:213], v142 offset:0x2800
	ds_read_b64_tr_b16 v[214:215], v142 offset:0x3000
	ds_read_b64_tr_b16 v[216:217], v142 offset:0x3800
	s_waitcnt lgkmcnt(6)
	s_nop 0
	v_mfma_f32_32x32x16_bf16 v[0:15], v[152:155], v[202:205], v[0:15]
	ds_read_b64_tr_b16 v[202:203], v142 offset:0x200
	ds_read_b64_tr_b16 v[204:205], v142 offset:0xa00
	s_waitcnt lgkmcnt(6)
	v_mfma_f32_32x32x16_bf16 v[0:15], v[160:163], v[206:209], v[0:15]
	ds_read_b64_tr_b16 v[206:207], v142 offset:0x1200
	ds_read_b64_tr_b16 v[208:209], v142 offset:0x1a00
	s_waitcnt lgkmcnt(6)
	v_mfma_f32_32x32x16_bf16 v[0:15], v[164:167], v[210:213], v[0:15]
	ds_read_b64_tr_b16 v[210:211], v142 offset:0x2200
	ds_read_b64_tr_b16 v[212:213], v142 offset:0x2a00
	s_waitcnt lgkmcnt(6)
	v_mfma_f32_32x32x16_bf16 v[0:15], v[168:171], v[214:217], v[0:15]
	ds_read_b64_tr_b16 v[214:215], v142 offset:0x3200
	ds_read_b64_tr_b16 v[216:217], v142 offset:0x3a00
	s_waitcnt lgkmcnt(6)
	v_mfma_f32_32x32x16_bf16 v[48:63], v[152:155], v[202:205], v[48:63]
	ds_read_b64_tr_b16 v[202:203], v142 offset:0x400
	ds_read_b64_tr_b16 v[204:205], v142 offset:0xc00
	s_waitcnt lgkmcnt(6)
	v_mfma_f32_32x32x16_bf16 v[48:63], v[160:163], v[206:209], v[48:63]
	ds_read_b64_tr_b16 v[206:207], v142 offset:0x1400
	ds_read_b64_tr_b16 v[208:209], v142 offset:0x1c00
	s_waitcnt lgkmcnt(6)
	v_mfma_f32_32x32x16_bf16 v[48:63], v[164:167], v[210:213], v[48:63]
	ds_read_b64_tr_b16 v[210:211], v142 offset:0x2400
	ds_read_b64_tr_b16 v[212:213], v142 offset:0x2c00
	s_waitcnt lgkmcnt(6)
	v_mfma_f32_32x32x16_bf16 v[48:63], v[168:171], v[214:217], v[48:63]
	ds_read_b64_tr_b16 v[214:215], v142 offset:0x3400
	ds_read_b64_tr_b16 v[216:217], v142 offset:0x3c00
	s_waitcnt lgkmcnt(6)
	v_mfma_f32_32x32x16_bf16 v[32:47], v[152:155], v[202:205], v[32:47]
	ds_read_b64_tr_b16 v[202:203], v142 offset:0x600
	ds_read_b64_tr_b16 v[204:205], v142 offset:0xe00
	s_waitcnt lgkmcnt(6)
	v_mfma_f32_32x32x16_bf16 v[32:47], v[160:163], v[206:209], v[32:47]
	ds_read_b64_tr_b16 v[206:207], v142 offset:0x1600
	ds_read_b64_tr_b16 v[208:209], v142 offset:0x1e00
	s_waitcnt lgkmcnt(6)
	v_mfma_f32_32x32x16_bf16 v[32:47], v[164:167], v[210:213], v[32:47]
	ds_read_b64_tr_b16 v[210:211], v142 offset:0x2600
	ds_read_b64_tr_b16 v[212:213], v142 offset:0x2e00
	s_waitcnt lgkmcnt(6)
	v_mfma_f32_32x32x16_bf16 v[32:47], v[168:171], v[214:217], v[32:47]
	ds_read_b64_tr_b16 v[214:215], v142 offset:0x3600
	ds_read_b64_tr_b16 v[216:217], v142 offset:0x3e00
	s_waitcnt lgkmcnt(6)
	v_mfma_f32_32x32x16_bf16 v[16:31], v[152:155], v[202:205], v[16:31]
	v_max_f32_e32 v142, v81, v81
	v_max_f32_e32 v152, v80, v80
	v_max_f32_e32 v142, v152, v142
	v_max3_f32 v142, v142, v82, v83
	v_max3_f32 v142, v142, v84, v85
	v_max3_f32 v142, v142, v86, v87
	v_max3_f32 v142, v142, v88, v89
	s_waitcnt lgkmcnt(4)
	v_mfma_f32_32x32x16_bf16 v[16:31], v[160:163], v[206:209], v[16:31]
	v_max3_f32 v142, v142, v90, v91
	v_max3_f32 v142, v142, v92, v93
	v_max3_f32 v142, v142, v94, v95
	v_max3_f32 v142, v142, v64, v65
	v_max3_f32 v142, v142, v66, v67
	v_max3_f32 v142, v142, v68, v69
	v_max3_f32 v142, v142, v70, v71
	s_waitcnt lgkmcnt(2)
	v_mfma_f32_32x32x16_bf16 v[16:31], v[164:167], v[210:213], v[16:31]
	v_max3_f32 v142, v142, v72, v73
	v_max3_f32 v142, v142, v74, v75
	v_max3_f32 v142, v142, v76, v77
	v_max3_f32 v142, v142, v78, v79
	v_mov_b32_e32 v152, v142
	s_nop 1
	v_permlane32_swap_b32_e32 v142, v152
	s_waitcnt lgkmcnt(0)
	v_mfma_f32_32x32x16_bf16 v[16:31], v[168:171], v[214:217], v[16:31]
	v_max_f32_e32 v152, v152, v152
	v_max_f32_e32 v142, v142, v142
	v_max_f32_e32 v142, v142, v152
	v_sub_f32_e32 v152, v142, v143
	v_cmp_ge_f32_e64 s[8:9], s40, v152
	s_mov_b64 s[24:25], -1
	s_and_b64 vcc, exec, s[22:23]
	s_cbranch_vccz .LBB0_112
	s_waitcnt vmcnt(0)
	s_mov_b64 s[24:25], 0

; __device__ __forceinline__ void finishSM(f32x16& p0, f32x16& p1, float alpha, float& l_reg, bf16x8& pa0, bf16x8& pa1, bf16x8& pa2, bf16x8& pa3) {
;   for (int r = 0; r < 16; ++r) p1[r] = __builtin_amdgcn_exp2f(p1[r]);
;   float ps = 0; for (int r = 0; r < 16; ++r) ps += p0[r]; for (int r = 0; r < 16; ++r) ps += p1[r];
;   { auto rr = __builtin_amdgcn_permlane32_swap(__float_as_uint(ps), __float_as_uint(ps), false, false);
;     ps = __uint_as_float(rr[0]) + __uint_as_float(rr[1]); }
;   l_reg = l_reg * alpha + ps;
;     ...
;   PK4(p0, 0, pa0); PK4(p0, 8, pa1); PK4(p1, 0, pa2); PK4(p1, 8, pa3);
; template <int qh> __device__ __forceinline__ void qkt(f32x16& p0, f32x16& p1, const bf16_t* Ks, const bf16x8* qr, int r32, int hi) {
;   p0 = f32x16{}; p1 = f32x16{};
;   if constexpr (qh != 2) { QKT_STEP(0); QKT_STEP(1); QKT_STEP(2); QKT_STEP(3); }
;   if constexpr (qh != 1) { QKT_STEP(4); QKT_STEP(5); QKT_STEP(6); QKT_STEP(7); }
.LBB0_132:
	s_add_i32 s8, s83, 0xffff8000
	s_and_b32 s36, s8, 0x18000
	s_add_i32 s8, s36, 0
	v_add_u32_e32 v68, s8, v179
	ds_read_b128 v[64:67], v68
	ds_read_b128 v[68:71], v68 offset:8192
	v_add_u32_e32 v198, s8, v180
	ds_read_b128 v[202:205], v198
	ds_read_b128 v[206:209], v198 offset:8192
	v_exp_f32_e32 v210, v134
	s_waitcnt lgkmcnt(0)
	v_mfma_f32_32x32x16_bf16 v[80:95], v[64:67], v[108:111], 0
	v_add_f32_e32 v134, 0, v162
	v_add_f32_e32 v134, v164, v134
	v_add_f32_e32 v134, v166, v134
	v_add_f32_e32 v134, v168, v134
	v_add_f32_e32 v134, v170, v134
	v_add_f32_e32 v134, v184, v134
	v_mfma_f32_32x32x16_bf16 v[64:79], v[68:71], v[108:111], 0
	v_add_f32_e32 v134, v185, v134
	v_add_f32_e32 v134, v200, v134
	v_add_f32_e32 v134, v160, v134
	v_add_f32_e32 v134, v161, v134
	v_add_f32_e32 v134, v163, v134
	v_add_f32_e32 v134, v165, v134
	v_exp_f32_e32 v154, v154
	v_mfma_f32_32x32x16_bf16 v[80:95], v[202:205], v[104:107], v[80:95]
	v_add_f32_e32 v134, v167, v134
	v_exp_f32_e32 v155, v155
	v_add_f32_e32 v134, v169, v134
	v_exp_f32_e32 v152, v152
	v_add_f32_e32 v134, v171, v134
	v_exp_f32_e32 v153, v153
	v_add_f32_e32 v134, v199, v134
	v_mfma_f32_32x32x16_bf16 v[64:79], v[206:209], v[104:107], v[64:79]
	v_add_u32_e32 v198, s8, v181
	ds_read_b128 v[202:205], v198
	ds_read_b128 v[206:209], v198 offset:8192
	v_add_u32_e32 v236, s8, v182
	ds_read_b128 v[228:231], v236
	ds_read_b128 v[232:235], v236 offset:8192
	v_add_f32_e32 v134, v154, v134
	v_exp_f32_e32 v201, v151
	v_add_f32_e32 v134, v155, v134
	v_add_f32_e32 v134, v152, v134
	v_add_f32_e32 v134, v153, v134
	s_waitcnt lgkmcnt(2)
	v_mfma_f32_32x32x16_bf16 v[80:95], v[202:205], v[100:103], v[80:95]
	v_exp_f32_e32 v211, v135
	v_cvt_pk_bf16_f32 v151, v152, v153
	v_mfma_f32_32x32x16_bf16 v[64:79], v[206:209], v[100:103], v[64:79]
	v_exp_f32_e32 v198, v150
	v_cvt_pk_bf16_f32 v150, v154, v155
	v_add_f32_e32 v134, v198, v134
	v_add_f32_e32 v134, v201, v134
	s_waitcnt lgkmcnt(0)
	v_mfma_f32_32x32x16_bf16 v[80:95], v[228:231], v[96:99], v[80:95]
	v_exp_f32_e32 v202, v142
	v_exp_f32_e32 v203, v143
	v_exp_f32_e32 v204, v140
	v_exp_f32_e32 v205, v141
	v_add_f32_e32 v134, v202, v134
	v_add_f32_e32 v134, v203, v134
	v_add_f32_e32 v134, v204, v134
	v_mfma_f32_32x32x16_bf16 v[64:79], v[232:235], v[96:99], v[64:79]
	v_exp_f32_e32 v206, v138
	v_exp_f32_e32 v207, v139
	v_exp_f32_e32 v208, v136
	v_exp_f32_e32 v209, v137
	v_add_f32_e32 v134, v205, v134
	v_add_f32_e32 v134, v206, v134
	v_add_f32_e32 v134, v207, v134
	v_add_f32_e32 v134, v208, v134
	v_add_f32_e32 v134, v209, v134
	v_add_f32_e32 v134, v210, v134
	v_add_f32_e32 v134, v211, v134
	v_mov_b32_e32 v135, v134
	v_cvt_pk_bf16_f32 v136, v162, v164
	v_cvt_pk_bf16_f32 v138, v170, v184
	v_permlane32_swap_b32_e32 v134, v135
	v_cvt_pk_bf16_f32 v137, v166, v168
	v_cvt_pk_bf16_f32 v139, v185, v200
	v_permlane32_swap_b32_e32 v136, v138
	v_cvt_pk_bf16_f32 v140, v160, v161
	v_cvt_pk_bf16_f32 v141, v163, v165
	v_cvt_pk_bf16_f32 v142, v167, v169
	v_cvt_pk_bf16_f32 v143, v171, v199
	v_cvt_pk_bf16_f32 v152, v198, v201
	v_cvt_pk_bf16_f32 v153, v202, v203
	v_cvt_pk_bf16_f32 v160, v204, v205
	v_cvt_pk_bf16_f32 v161, v206, v207
	v_cvt_pk_bf16_f32 v162, v208, v209
	v_cvt_pk_bf16_f32 v163, v210, v211
	v_permlane32_swap_b32_e32 v137, v139
	v_permlane32_swap_b32_e32 v140, v142
	v_permlane32_swap_b32_e32 v141, v143
	v_permlane32_swap_b32_e32 v150, v152
	v_permlane32_swap_b32_e32 v151, v153
	v_permlane32_swap_b32_e32 v160, v162
	v_permlane32_swap_b32_e32 v161, v163
	s_add_i32 s15, s83, 0x10000
	s_and_b32 s38, s15, 0x18000
	v_add_u32_e32 v154, s38, v173
	ds_read_b64_tr_b16 v[164:165], v154 offset:0
	ds_read_b64_tr_b16 v[166:167], v154 offset:0x800
	ds_read_b64_tr_b16 v[168:169], v154 offset:0x1000
	ds_read_b64_tr_b16 v[170:171], v154 offset:0x1800
	ds_read_b64_tr_b16 v[200:201], v154 offset:0x2000
	ds_read_b64_tr_b16 v[202:203], v154 offset:0x2800
	ds_read_b64_tr_b16 v[204:205], v154 offset:0x3000
	ds_read_b64_tr_b16 v[206:207], v154 offset:0x3800
	s_waitcnt lgkmcnt(6)
; #define SBAR() __builtin_amdgcn_sched_barrier(0)
; __device__ __forceinline__ void partialSM(f32x16& p0, f32x16& p1, float& m_reg, float& mn, float& alpha, float C, float thr) {
;   float pmax = p0[0]; for (int r = 1; r < 16; ++r) pmax = fmaxf(pmax, p0[r]); for (int r = 0; r < 16; ++r) pmax = fmaxf(pmax, p1[r]);
;   { auto rr = __builtin_amdgcn_permlane32_swap(__float_as_uint(pmax), __float_as_uint(pmax), false, false);
;     pmax = fmaxf(__uint_as_float(rr[0]), __uint_as_float(rr[1])); }
;   if (__builtin_expect(__all(pmax - m_reg <= thr), 1)) { mn = m_reg; alpha = 1.f; }
; template <int D0> __device__ __forceinline__ void pv_one(f32x16& od, int vb, bf16x8 pa0, bf16x8 pa1, bf16x8 pa2, bf16x8 pa3) {
;   const s16x4 l0 = tr_read<v_rd_off(D0, 0, 0)>(vb), h0 = tr_read<v_rd_off(D0, 0, 1)>(vb), l1 = tr_read<v_rd_off(D0, 1, 0)>(vb), h1 = tr_read<v_rd_off(D0, 1, 1)>(vb);
;   const s16x4 l2 = tr_read<v_rd_off(D0, 2, 0)>(vb), h2 = tr_read<v_rd_off(D0, 2, 1)>(vb), l3 = tr_read<v_rd_off(D0, 3, 0)>(vb), h3 = tr_read<v_rd_off(D0, 3, 1)>(vb);
;   asm volatile("s_waitcnt lgkmcnt(0)" ::: "memory"); SBAR();
;     ...
;   od = __builtin_amdgcn_mfma_f32_32x32x16_bf16(pa0, PK(l0, h0), od, 0, 0, 0);
;   od = __builtin_amdgcn_mfma_f32_32x32x16_bf16(pa1, PK(l1, h1), od, 0, 0, 0);
;   od = __builtin_amdgcn_mfma_f32_32x32x16_bf16(pa2, PK(l2, h2), od, 0, 0, 0);
;   od = __builtin_amdgcn_mfma_f32_32x32x16_bf16(pa3, PK(l3, h3), od, 0, 0, 0);
;     ...
; }
; __device__ __forceinline__ void pv_d0(f32x16* o, int vb, bf16x8 pa0, bf16x8 pa1, bf16x8 pa2, bf16x8 pa3) {
;   pv_one<0>(o[0], vb, pa0, pa1, pa2, pa3); pv_one<1>(o[1], vb, pa0, pa1, pa2, pa3); pv_one<2>(o[2], vb, pa0, pa1, pa2, pa3); pv_one<3>(o[3], vb, pa0, pa1, pa2, pa3);
	s_nop 0
	v_mfma_f32_32x32x16_bf16 v[0:15], v[136:139], v[164:167], v[0:15]
	ds_read_b64_tr_b16 v[164:165], v154 offset:0x200
	ds_read_b64_tr_b16 v[166:167], v154 offset:0xa00
	s_waitcnt lgkmcnt(6)
	v_mfma_f32_32x32x16_bf16 v[0:15], v[140:143], v[168:171], v[0:15]
	ds_read_b64_tr_b16 v[168:169], v154 offset:0x1200
	ds_read_b64_tr_b16 v[170:171], v154 offset:0x1a00
	s_waitcnt lgkmcnt(6)
	v_mfma_f32_32x32x16_bf16 v[0:15], v[150:153], v[200:203], v[0:15]
	ds_read_b64_tr_b16 v[200:201], v154 offset:0x2200
	ds_read_b64_tr_b16 v[202:203], v154 offset:0x2a00
	s_waitcnt lgkmcnt(6)
	v_mfma_f32_32x32x16_bf16 v[0:15], v[160:163], v[204:207], v[0:15]
	ds_read_b64_tr_b16 v[204:205], v154 offset:0x3200
	ds_read_b64_tr_b16 v[206:207], v154 offset:0x3a00
	s_waitcnt lgkmcnt(6)
	v_mfma_f32_32x32x16_bf16 v[48:63], v[136:139], v[164:167], v[48:63]
	ds_read_b64_tr_b16 v[164:165], v154 offset:0x400
	ds_read_b64_tr_b16 v[166:167], v154 offset:0xc00
	s_waitcnt lgkmcnt(6)
	v_mfma_f32_32x32x16_bf16 v[48:63], v[140:143], v[168:171], v[48:63]
	ds_read_b64_tr_b16 v[168:169], v154 offset:0x1400
	ds_read_b64_tr_b16 v[170:171], v154 offset:0x1c00
	s_waitcnt lgkmcnt(6)
	v_mfma_f32_32x32x16_bf16 v[48:63], v[150:153], v[200:203], v[48:63]
	ds_read_b64_tr_b16 v[200:201], v154 offset:0x2400
	ds_read_b64_tr_b16 v[202:203], v154 offset:0x2c00
	s_waitcnt lgkmcnt(6)
	v_mfma_f32_32x32x16_bf16 v[48:63], v[160:163], v[204:207], v[48:63]
	ds_read_b64_tr_b16 v[204:205], v154 offset:0x3400
	ds_read_b64_tr_b16 v[206:207], v154 offset:0x3c00
	s_waitcnt lgkmcnt(6)
	v_mfma_f32_32x32x16_bf16 v[32:47], v[136:139], v[164:167], v[32:47]
	ds_read_b64_tr_b16 v[164:165], v154 offset:0x600
	ds_read_b64_tr_b16 v[166:167], v154 offset:0xe00
	s_waitcnt lgkmcnt(6)
	v_mfma_f32_32x32x16_bf16 v[32:47], v[140:143], v[168:171], v[32:47]
	ds_read_b64_tr_b16 v[168:169], v154 offset:0x1600
	ds_read_b64_tr_b16 v[170:171], v154 offset:0x1e00
	s_waitcnt lgkmcnt(6)
	v_mfma_f32_32x32x16_bf16 v[32:47], v[150:153], v[200:203], v[32:47]
	ds_read_b64_tr_b16 v[200:201], v154 offset:0x2600
	ds_read_b64_tr_b16 v[202:203], v154 offset:0x2e00
	s_waitcnt lgkmcnt(6)
	v_mfma_f32_32x32x16_bf16 v[32:47], v[160:163], v[204:207], v[32:47]
	ds_read_b64_tr_b16 v[204:205], v154 offset:0x3600
	ds_read_b64_tr_b16 v[206:207], v154 offset:0x3e00
	s_waitcnt lgkmcnt(6)
	v_mfma_f32_32x32x16_bf16 v[16:31], v[136:139], v[164:167], v[16:31]
	v_max_f32_e32 v136, v81, v81
	v_max_f32_e32 v137, v80, v80
	v_max_f32_e32 v136, v137, v136
	v_max3_f32 v136, v136, v82, v83
	v_max3_f32 v136, v136, v84, v85
	v_max3_f32 v136, v136, v86, v87
	v_max3_f32 v136, v136, v88, v89
	s_waitcnt lgkmcnt(4)
	v_mfma_f32_32x32x16_bf16 v[16:31], v[140:143], v[168:171], v[16:31]
	v_max3_f32 v136, v136, v90, v91
	v_max3_f32 v136, v136, v92, v93
	v_max3_f32 v136, v136, v94, v95
	v_max3_f32 v136, v136, v64, v65
	v_max3_f32 v136, v136, v66, v67
	v_max3_f32 v136, v136, v68, v69
	v_max3_f32 v136, v136, v70, v71
	s_waitcnt lgkmcnt(2)
	v_mfma_f32_32x32x16_bf16 v[16:31], v[150:153], v[200:203], v[16:31]
	v_max3_f32 v136, v136, v72, v73
	v_max3_f32 v136, v136, v74, v75
	v_max3_f32 v136, v136, v76, v77
	v_max3_f32 v136, v136, v78, v79
	v_mov_b32_e32 v137, v136
	s_nop 1
	v_permlane32_swap_b32_e32 v136, v137
	s_waitcnt lgkmcnt(0)
	v_mfma_f32_32x32x16_bf16 v[16:31], v[160:163], v[204:207], v[16:31]
	v_max_f32_e32 v137, v137, v137
	v_max_f32_e32 v136, v136, v136
	v_max_f32_e32 v136, v136, v137
	v_sub_f32_e32 v137, v136, v158
	v_cmp_ge_f32_e64 s[8:9], s40, v137
	s_mov_b64 s[26:27], -1
	s_and_b64 vcc, exec, s[24:25]
	s_cbranch_vccz .LBB0_134
	s_waitcnt vmcnt(0)
	s_mov_b64 s[26:27], 0

; __device__ __forceinline__ void partialSM(f32x16& p0, f32x16& p1, float& m_reg, float& mn, float& alpha, float C, float thr) {
;     ...
;   else { mn = fmaxf(m_reg, pmax); alpha = __builtin_amdgcn_exp2f((m_reg - mn) * C); m_reg = mn; }
;   float mnC = -mn * C;
;   for (int r = 0; r < 16; ++r) p0[r] = fmaf(p0[r], C, mnC); for (int r = 0; r < 16; ++r) p1[r] = fmaf(p1[r], C, mnC);
;   for (int r = 0; r < 16; ++r) p0[r] = __builtin_amdgcn_exp2f(p0[r]);
; template <int qh> __device__ __forceinline__ void qkt(f32x16& p0, f32x16& p1, const bf16_t* Ks, const bf16x8* qr, int r32, int hi) {
;   p0 = f32x16{}; p1 = f32x16{};
;   if constexpr (qh != 2) { QKT_STEP(0); QKT_STEP(1); QKT_STEP(2); QKT_STEP(3); }
;   if constexpr (qh != 1) { QKT_STEP(4); QKT_STEP(5); QKT_STEP(6); QKT_STEP(7); }
.LBB0_142:
	v_cndmask_b32_e64 v121, v137, v158, s[8:9]
	v_mul_f32_e32 v120, 0xbfb8aa3b, v121
	v_fmamk_f32 v80, v80, 0x3fb8aa3b, v120
	v_fmamk_f32 v81, v81, 0x3fb8aa3b, v120
	v_fmamk_f32 v82, v82, 0x3fb8aa3b, v120
	v_fmamk_f32 v83, v83, 0x3fb8aa3b, v120
	v_fmamk_f32 v84, v84, 0x3fb8aa3b, v120
	v_fmamk_f32 v85, v85, 0x3fb8aa3b, v120
	v_fmamk_f32 v86, v86, 0x3fb8aa3b, v120
	v_fmamk_f32 v87, v87, 0x3fb8aa3b, v120
	v_fmamk_f32 v88, v88, 0x3fb8aa3b, v120
	v_fmamk_f32 v89, v89, 0x3fb8aa3b, v120
	v_fmamk_f32 v90, v90, 0x3fb8aa3b, v120
	v_fmamk_f32 v91, v91, 0x3fb8aa3b, v120
	v_fmamk_f32 v92, v92, 0x3fb8aa3b, v120
	v_fmamk_f32 v93, v93, 0x3fb8aa3b, v120
	v_fmamk_f32 v94, v94, 0x3fb8aa3b, v120
	v_fmamk_f32 v95, v95, 0x3fb8aa3b, v120
	v_fmamk_f32 v126, v64, 0x3fb8aa3b, v120
	v_fmamk_f32 v127, v65, 0x3fb8aa3b, v120
	v_fmamk_f32 v137, v66, 0x3fb8aa3b, v120
	v_fmamk_f32 v142, v67, 0x3fb8aa3b, v120
	v_fmamk_f32 v143, v68, 0x3fb8aa3b, v120
	v_fmamk_f32 v150, v69, 0x3fb8aa3b, v120
	v_fmamk_f32 v151, v70, 0x3fb8aa3b, v120
	v_fmamk_f32 v152, v71, 0x3fb8aa3b, v120
	v_fmamk_f32 v153, v72, 0x3fb8aa3b, v120
	v_fmamk_f32 v154, v73, 0x3fb8aa3b, v120
	v_fmamk_f32 v155, v74, 0x3fb8aa3b, v120
	v_fmamk_f32 v158, v75, 0x3fb8aa3b, v120
	v_fmamk_f32 v160, v76, 0x3fb8aa3b, v120
	v_fmamk_f32 v201, v77, 0x3fb8aa3b, v120
	v_fmamk_f32 v202, v78, 0x3fb8aa3b, v120
	v_fmac_f32_e32 v120, 0x3fb8aa3b, v79
	v_exp_f32_e32 v161, v80
	v_exp_f32_e32 v162, v81
	v_exp_f32_e32 v163, v82
	v_exp_f32_e32 v164, v83
	v_exp_f32_e32 v165, v84
	v_exp_f32_e32 v166, v85
	v_exp_f32_e32 v167, v86
	v_exp_f32_e32 v168, v87
	v_exp_f32_e32 v169, v88
	v_exp_f32_e32 v170, v89
	v_exp_f32_e32 v171, v90
	v_exp_f32_e32 v184, v91
	v_exp_f32_e32 v185, v92
	v_exp_f32_e32 v198, v93
	v_exp_f32_e32 v199, v94
	v_exp_f32_e32 v200, v95
	s_and_b32 s8, s83, 0x18000
	s_add_i32 s8, s8, 0
	v_add_u32_e32 v68, s8, v179
	ds_read_b128 v[64:67], v68
	ds_read_b128 v[68:71], v68 offset:8192
	v_add_u32_e32 v138, s8, v180
	ds_read_b128 v[122:125], v138
	ds_read_b128 v[138:141], v138 offset:8192
	v_exp_f32_e32 v203, v126
	s_waitcnt lgkmcnt(0)
	v_mfma_f32_32x32x16_bf16 v[80:95], v[64:67], v[108:111], 0
	v_exp_f32_e32 v204, v127
	v_exp_f32_e32 v137, v137
	v_exp_f32_e32 v142, v142
	v_exp_f32_e32 v143, v143
	v_exp_f32_e32 v205, v150
	v_exp_f32_e32 v206, v151
	v_exp_f32_e32 v207, v152
	v_mfma_f32_32x32x16_bf16 v[64:79], v[68:71], v[108:111], 0
	v_exp_f32_e32 v208, v153
	v_exp_f32_e32 v154, v154
	v_exp_f32_e32 v155, v155
	v_exp_f32_e32 v158, v158
	v_exp_f32_e32 v209, v160
	v_exp_f32_e32 v201, v201
	v_exp_f32_e32 v202, v202
	v_mfma_f32_32x32x16_bf16 v[80:95], v[122:125], v[104:107], v[80:95]
	v_exp_f32_e32 v120, v120
	v_cvt_pk_bf16_f32 v126, v165, v166
	v_cvt_pk_bf16_f32 v127, v167, v168
	v_cvt_pk_bf16_f32 v150, v203, v204
	v_cvt_pk_bf16_f32 v151, v137, v142
	v_cvt_pk_bf16_f32 v152, v143, v205
	v_cvt_pk_bf16_f32 v153, v206, v207
	v_mfma_f32_32x32x16_bf16 v[64:79], v[138:141], v[104:107], v[64:79]
	v_add_u32_e32 v138, s8, v181
	ds_read_b128 v[122:125], v138
	ds_read_b128 v[138:141], v138 offset:8192
	v_add_u32_e32 v236, s8, v182
	ds_read_b128 v[228:231], v236
	ds_read_b128 v[232:235], v236 offset:8192
	v_cvt_pk_bf16_f32 v160, v208, v154
	v_permlane32_swap_b32_e32 v150, v152
	v_permlane32_swap_b32_e32 v151, v153
	s_waitcnt lgkmcnt(2)
	v_mfma_f32_32x32x16_bf16 v[80:95], v[122:125], v[100:103], v[80:95]
	v_mfma_f32_32x32x16_bf16 v[64:79], v[138:141], v[100:103], v[64:79]
	s_waitcnt lgkmcnt(0)
	v_mfma_f32_32x32x16_bf16 v[80:95], v[228:231], v[96:99], v[80:95]
	v_add_f32_e32 v122, 0, v161
	v_add_f32_e32 v122, v162, v122
	v_add_f32_e32 v122, v163, v122
	v_add_f32_e32 v122, v164, v122
	v_add_f32_e32 v122, v165, v122
	v_add_f32_e32 v122, v166, v122
	v_add_f32_e32 v122, v167, v122
	v_add_f32_e32 v122, v168, v122
	v_add_f32_e32 v122, v169, v122
	v_add_f32_e32 v122, v170, v122
	v_add_f32_e32 v122, v171, v122
	v_add_f32_e32 v122, v184, v122
	v_add_f32_e32 v122, v185, v122
	v_add_f32_e32 v122, v198, v122
	v_add_f32_e32 v122, v199, v122
	v_add_f32_e32 v122, v200, v122
	v_add_f32_e32 v122, v203, v122
	v_add_f32_e32 v122, v204, v122
	v_add_f32_e32 v122, v137, v122
	v_add_f32_e32 v122, v142, v122
	v_add_f32_e32 v122, v143, v122
	v_add_f32_e32 v122, v205, v122
	v_add_f32_e32 v122, v206, v122
	v_add_f32_e32 v122, v207, v122
	v_add_f32_e32 v122, v208, v122
	v_add_f32_e32 v122, v154, v122
	v_mfma_f32_32x32x16_bf16 v[64:79], v[232:235], v[96:99], v[64:79]
	v_add_f32_e32 v122, v155, v122
	v_add_f32_e32 v122, v158, v122
	v_add_f32_e32 v122, v209, v122
	v_add_f32_e32 v122, v201, v122
	v_add_f32_e32 v122, v202, v122
	v_add_f32_e32 v122, v120, v122
	v_mov_b32_e32 v123, v122
	s_nop 1
	v_permlane32_swap_b32_e32 v122, v123
	v_cvt_pk_bf16_f32 v124, v161, v162
	v_cvt_pk_bf16_f32 v125, v163, v164
	v_cvt_pk_bf16_f32 v138, v169, v170
	v_cvt_pk_bf16_f32 v139, v171, v184
	v_cvt_pk_bf16_f32 v140, v185, v198
	v_cvt_pk_bf16_f32 v141, v199, v200
	v_cvt_pk_bf16_f32 v161, v155, v158
	v_cvt_pk_bf16_f32 v162, v209, v201
	v_cvt_pk_bf16_f32 v163, v202, v120
	v_permlane32_swap_b32_e32 v124, v126
	v_permlane32_swap_b32_e32 v125, v127
	v_permlane32_swap_b32_e32 v138, v140
	v_permlane32_swap_b32_e32 v139, v141
	v_permlane32_swap_b32_e32 v160, v162
	v_permlane32_swap_b32_e32 v161, v163
	v_add_u32_e32 v120, s36, v173
	ds_read_b64_tr_b16 v[164:165], v120 offset:0
	ds_read_b64_tr_b16 v[166:167], v120 offset:0x800
	ds_read_b64_tr_b16 v[168:169], v120 offset:0x1000
	ds_read_b64_tr_b16 v[170:171], v120 offset:0x1800
	ds_read_b64_tr_b16 v[200:201], v120 offset:0x2000
	ds_read_b64_tr_b16 v[202:203], v120 offset:0x2800
	ds_read_b64_tr_b16 v[204:205], v120 offset:0x3000
	ds_read_b64_tr_b16 v[206:207], v120 offset:0x3800
	s_waitcnt lgkmcnt(6)
; #define SBAR() __builtin_amdgcn_sched_barrier(0)
; __device__ __forceinline__ void partialSM(f32x16& p0, f32x16& p1, float& m_reg, float& mn, float& alpha, float C, float thr) {
;   float pmax = p0[0]; for (int r = 1; r < 16; ++r) pmax = fmaxf(pmax, p0[r]); for (int r = 0; r < 16; ++r) pmax = fmaxf(pmax, p1[r]);
;   { auto rr = __builtin_amdgcn_permlane32_swap(__float_as_uint(pmax), __float_as_uint(pmax), false, false);
;     pmax = fmaxf(__uint_as_float(rr[0]), __uint_as_float(rr[1])); }
;   if (__builtin_expect(__all(pmax - m_reg <= thr), 1)) { mn = m_reg; alpha = 1.f; }
; template <int D0> __device__ __forceinline__ void pv_one(f32x16& od, int vb, bf16x8 pa0, bf16x8 pa1, bf16x8 pa2, bf16x8 pa3) {
;   const s16x4 l0 = tr_read<v_rd_off(D0, 0, 0)>(vb), h0 = tr_read<v_rd_off(D0, 0, 1)>(vb), l1 = tr_read<v_rd_off(D0, 1, 0)>(vb), h1 = tr_read<v_rd_off(D0, 1, 1)>(vb);
;   const s16x4 l2 = tr_read<v_rd_off(D0, 2, 0)>(vb), h2 = tr_read<v_rd_off(D0, 2, 1)>(vb), l3 = tr_read<v_rd_off(D0, 3, 0)>(vb), h3 = tr_read<v_rd_off(D0, 3, 1)>(vb);
;   asm volatile("s_waitcnt lgkmcnt(0)" ::: "memory"); SBAR();
;     ...
;   od = __builtin_amdgcn_mfma_f32_32x32x16_bf16(pa0, PK(l0, h0), od, 0, 0, 0);
;   od = __builtin_amdgcn_mfma_f32_32x32x16_bf16(pa1, PK(l1, h1), od, 0, 0, 0);
;   od = __builtin_amdgcn_mfma_f32_32x32x16_bf16(pa2, PK(l2, h2), od, 0, 0, 0);
;   od = __builtin_amdgcn_mfma_f32_32x32x16_bf16(pa3, PK(l3, h3), od, 0, 0, 0);
;     ...
; }
; __device__ __forceinline__ void pv_d0(f32x16* o, int vb, bf16x8 pa0, bf16x8 pa1, bf16x8 pa2, bf16x8 pa3) {
;   pv_one<0>(o[0], vb, pa0, pa1, pa2, pa3); pv_one<1>(o[1], vb, pa0, pa1, pa2, pa3); pv_one<2>(o[2], vb, pa0, pa1, pa2, pa3); pv_one<3>(o[3], vb, pa0, pa1, pa2, pa3);
	s_nop 0
	v_mfma_f32_32x32x16_bf16 v[0:15], v[124:127], v[164:167], v[0:15]
	ds_read_b64_tr_b16 v[164:165], v120 offset:0x200
	ds_read_b64_tr_b16 v[166:167], v120 offset:0xa00
	s_waitcnt lgkmcnt(6)
	v_mfma_f32_32x32x16_bf16 v[0:15], v[138:141], v[168:171], v[0:15]
	ds_read_b64_tr_b16 v[168:169], v120 offset:0x1200
	ds_read_b64_tr_b16 v[170:171], v120 offset:0x1a00
	s_waitcnt lgkmcnt(6)
	v_mfma_f32_32x32x16_bf16 v[0:15], v[150:153], v[200:203], v[0:15]
	ds_read_b64_tr_b16 v[200:201], v120 offset:0x2200
	ds_read_b64_tr_b16 v[202:203], v120 offset:0x2a00
	s_waitcnt lgkmcnt(6)
	v_mfma_f32_32x32x16_bf16 v[0:15], v[160:163], v[204:207], v[0:15]
	ds_read_b64_tr_b16 v[204:205], v120 offset:0x3200
	ds_read_b64_tr_b16 v[206:207], v120 offset:0x3a00
	s_waitcnt lgkmcnt(6)
	v_mfma_f32_32x32x16_bf16 v[48:63], v[124:127], v[164:167], v[48:63]
	ds_read_b64_tr_b16 v[164:165], v120 offset:0x400
	ds_read_b64_tr_b16 v[166:167], v120 offset:0xc00
	s_waitcnt lgkmcnt(6)
	v_mfma_f32_32x32x16_bf16 v[48:63], v[138:141], v[168:171], v[48:63]
	ds_read_b64_tr_b16 v[168:169], v120 offset:0x1400
	ds_read_b64_tr_b16 v[170:171], v120 offset:0x1c00
	s_waitcnt lgkmcnt(6)
	v_mfma_f32_32x32x16_bf16 v[48:63], v[150:153], v[200:203], v[48:63]
	ds_read_b64_tr_b16 v[200:201], v120 offset:0x2400
	ds_read_b64_tr_b16 v[202:203], v120 offset:0x2c00
	s_waitcnt lgkmcnt(6)
	v_mfma_f32_32x32x16_bf16 v[48:63], v[160:163], v[204:207], v[48:63]
	ds_read_b64_tr_b16 v[204:205], v120 offset:0x3400
	ds_read_b64_tr_b16 v[206:207], v120 offset:0x3c00
	s_waitcnt lgkmcnt(6)
	v_mfma_f32_32x32x16_bf16 v[32:47], v[124:127], v[164:167], v[32:47]
	ds_read_b64_tr_b16 v[164:165], v120 offset:0x600
	ds_read_b64_tr_b16 v[166:167], v120 offset:0xe00
	s_waitcnt lgkmcnt(6)
	v_mfma_f32_32x32x16_bf16 v[32:47], v[138:141], v[168:171], v[32:47]
	ds_read_b64_tr_b16 v[168:169], v120 offset:0x1600
	ds_read_b64_tr_b16 v[170:171], v120 offset:0x1e00
	s_waitcnt lgkmcnt(6)
	v_mfma_f32_32x32x16_bf16 v[32:47], v[150:153], v[200:203], v[32:47]
	ds_read_b64_tr_b16 v[200:201], v120 offset:0x2600
	ds_read_b64_tr_b16 v[202:203], v120 offset:0x2e00
	s_waitcnt lgkmcnt(6)
	v_mfma_f32_32x32x16_bf16 v[32:47], v[160:163], v[204:207], v[32:47]
	ds_read_b64_tr_b16 v[204:205], v120 offset:0x3600
	ds_read_b64_tr_b16 v[206:207], v120 offset:0x3e00
	s_waitcnt lgkmcnt(6)
	v_mfma_f32_32x32x16_bf16 v[16:31], v[124:127], v[164:167], v[16:31]
	v_max_f32_e32 v120, v81, v81
	v_max_f32_e32 v124, v80, v80
	v_max_f32_e32 v120, v124, v120
	v_max3_f32 v120, v120, v82, v83
	v_max3_f32 v120, v120, v84, v85
	v_max3_f32 v120, v120, v86, v87
	v_max3_f32 v120, v120, v88, v89
	s_waitcnt lgkmcnt(4)
	v_mfma_f32_32x32x16_bf16 v[16:31], v[138:141], v[168:171], v[16:31]
	v_max3_f32 v120, v120, v90, v91
	v_max3_f32 v120, v120, v92, v93
	v_max3_f32 v120, v120, v94, v95
	v_max3_f32 v120, v120, v64, v65
	v_max3_f32 v120, v120, v66, v67
	v_max3_f32 v120, v120, v68, v69
	v_max3_f32 v120, v120, v70, v71
	s_waitcnt lgkmcnt(2)
	v_mfma_f32_32x32x16_bf16 v[16:31], v[150:153], v[200:203], v[16:31]
	v_max3_f32 v120, v120, v72, v73
	v_max3_f32 v120, v120, v74, v75
	v_max3_f32 v120, v120, v76, v77
	v_max3_f32 v120, v120, v78, v79
	v_mov_b32_e32 v124, v120
	s_nop 1
	v_permlane32_swap_b32_e32 v120, v124
	s_waitcnt lgkmcnt(0)
	v_mfma_f32_32x32x16_bf16 v[16:31], v[160:163], v[204:207], v[16:31]
	v_max_f32_e32 v124, v124, v124
	v_max_f32_e32 v120, v120, v120
	v_max_f32_e32 v120, v120, v124
	v_sub_f32_e32 v124, v120, v121
	v_cmp_ge_f32_e64 s[8:9], s40, v124
	s_mov_b64 s[26:27], -1
	s_and_b64 vcc, exec, s[24:25]
	s_cbranch_vccz .LBB0_144
	s_waitcnt vmcnt(0)
	s_mov_b64 s[26:27], 0

; __device__ __forceinline__ void finishSM(f32x16& p0, f32x16& p1, float alpha, float& l_reg, bf16x8& pa0, bf16x8& pa1, bf16x8& pa2, bf16x8& pa3) {
;   for (int r = 0; r < 16; ++r) p1[r] = __builtin_amdgcn_exp2f(p1[r]);
;   float ps = 0; for (int r = 0; r < 16; ++r) ps += p0[r]; for (int r = 0; r < 16; ++r) ps += p1[r];
;   { auto rr = __builtin_amdgcn_permlane32_swap(__float_as_uint(ps), __float_as_uint(ps), false, false);
;     ps = __uint_as_float(rr[0]) + __uint_as_float(rr[1]); }
;   l_reg = l_reg * alpha + ps;
;     ...
;   PK4(p0, 0, pa0); PK4(p0, 8, pa1); PK4(p1, 0, pa2); PK4(p1, 8, pa3);
; template <int qh> __device__ __forceinline__ void qkt(f32x16& p0, f32x16& p1, const bf16_t* Ks, const bf16x8* qr, int r32, int hi) {
;   p0 = f32x16{}; p1 = f32x16{};
;   if constexpr (qh != 2) { QKT_STEP(0); QKT_STEP(1); QKT_STEP(2); QKT_STEP(3); }
;   if constexpr (qh != 1) { QKT_STEP(4); QKT_STEP(5); QKT_STEP(6); QKT_STEP(7); }
; }
.LBB0_163:
	s_add_i32 s8, s23, 0xffff8000
	s_and_b32 s24, s8, 0x18000
	s_add_i32 s8, s24, 0
	v_add_u32_e32 v68, s8, v175
	ds_read_b128 v[64:67], v68
	ds_read_b128 v[68:71], v68 offset:8192
	v_add_u32_e32 v198, s8, v176
	ds_read_b128 v[200:203], v198
	ds_read_b128 v[204:207], v198 offset:8192
	v_exp_f32_e32 v209, v134
	s_waitcnt lgkmcnt(0)
	v_mfma_f32_32x32x16_bf16 v[80:95], v[64:67], v[108:111], 0
	v_add_f32_e32 v134, 0, v161
	v_add_f32_e32 v134, v163, v134
	v_add_f32_e32 v134, v165, v134
	v_add_f32_e32 v134, v167, v134
	v_add_f32_e32 v134, v169, v134
	v_add_f32_e32 v134, v171, v134
	v_mfma_f32_32x32x16_bf16 v[64:79], v[68:71], v[108:111], 0
	v_add_f32_e32 v134, v184, v134
	v_add_f32_e32 v134, v199, v134
	v_add_f32_e32 v134, v159, v134
	v_add_f32_e32 v134, v160, v134
	v_add_f32_e32 v134, v162, v134
	v_add_f32_e32 v134, v164, v134
	v_exp_f32_e32 v154, v154
	v_mfma_f32_32x32x16_bf16 v[80:95], v[200:203], v[104:107], v[80:95]
	v_add_f32_e32 v134, v166, v134
	v_exp_f32_e32 v155, v155
	v_add_f32_e32 v134, v168, v134
	v_exp_f32_e32 v152, v152
	v_add_f32_e32 v134, v170, v134
	v_exp_f32_e32 v153, v153
	v_add_f32_e32 v134, v185, v134
	v_mfma_f32_32x32x16_bf16 v[64:79], v[204:207], v[104:107], v[64:79]
	v_add_u32_e32 v198, s8, v177
	ds_read_b128 v[200:203], v198
	ds_read_b128 v[204:207], v198 offset:8192
	v_add_u32_e32 v236, s8, v178
	ds_read_b128 v[228:231], v236
	ds_read_b128 v[232:235], v236 offset:8192
	v_add_f32_e32 v134, v154, v134
	v_add_f32_e32 v134, v155, v134
	v_add_f32_e32 v134, v152, v134
	v_add_f32_e32 v134, v153, v134
	v_exp_f32_e32 v208, v137
	s_waitcnt lgkmcnt(2)
	v_mfma_f32_32x32x16_bf16 v[80:95], v[200:203], v[100:103], v[80:95]
	v_exp_f32_e32 v210, v135
	v_cvt_pk_bf16_f32 v137, v165, v167
	v_mfma_f32_32x32x16_bf16 v[64:79], v[204:207], v[100:103], v[64:79]
	v_exp_f32_e32 v198, v150
	v_cvt_pk_bf16_f32 v150, v154, v155
	v_add_f32_e32 v134, v198, v134
	s_waitcnt lgkmcnt(0)
	v_mfma_f32_32x32x16_bf16 v[80:95], v[228:231], v[96:99], v[80:95]
	v_exp_f32_e32 v200, v151
	v_exp_f32_e32 v201, v142
	v_exp_f32_e32 v202, v143
	v_exp_f32_e32 v203, v140
	v_add_f32_e32 v134, v200, v134
	v_add_f32_e32 v134, v201, v134
	v_add_f32_e32 v134, v202, v134
	v_mfma_f32_32x32x16_bf16 v[64:79], v[232:235], v[96:99], v[64:79]
	v_exp_f32_e32 v204, v141
	v_exp_f32_e32 v205, v138
	v_exp_f32_e32 v206, v139
	v_exp_f32_e32 v207, v136
	v_add_f32_e32 v134, v203, v134
	v_add_f32_e32 v134, v204, v134
	v_add_f32_e32 v134, v205, v134
	v_add_f32_e32 v134, v206, v134
	v_add_f32_e32 v134, v207, v134
	v_add_f32_e32 v134, v208, v134
	v_add_f32_e32 v134, v209, v134
	v_add_f32_e32 v134, v210, v134
	v_mov_b32_e32 v135, v134
	v_cvt_pk_bf16_f32 v136, v161, v163
	v_cvt_pk_bf16_f32 v138, v169, v171
	v_permlane32_swap_b32_e32 v134, v135
	v_cvt_pk_bf16_f32 v139, v184, v199
	v_permlane32_swap_b32_e32 v136, v138
	v_cvt_pk_bf16_f32 v140, v159, v160
	v_cvt_pk_bf16_f32 v141, v162, v164
	v_cvt_pk_bf16_f32 v142, v166, v168
	v_cvt_pk_bf16_f32 v143, v170, v185
	v_cvt_pk_bf16_f32 v151, v152, v153
	v_cvt_pk_bf16_f32 v152, v198, v200
	v_cvt_pk_bf16_f32 v153, v201, v202
	v_cvt_pk_bf16_f32 v160, v203, v204
	v_cvt_pk_bf16_f32 v161, v205, v206
	v_cvt_pk_bf16_f32 v162, v207, v208
	v_cvt_pk_bf16_f32 v163, v209, v210
	v_permlane32_swap_b32_e32 v137, v139
	v_permlane32_swap_b32_e32 v140, v142
	v_permlane32_swap_b32_e32 v141, v143
	v_permlane32_swap_b32_e32 v150, v152
	v_permlane32_swap_b32_e32 v151, v153
	v_permlane32_swap_b32_e32 v160, v162
	v_permlane32_swap_b32_e32 v161, v163
	s_add_i32 s22, s23, 0x10000
	s_and_b32 s25, s22, 0x18000
	v_add_u32_e32 v154, s25, v173
	ds_read_b64_tr_b16 v[164:165], v154 offset:0
	ds_read_b64_tr_b16 v[166:167], v154 offset:0x800
	ds_read_b64_tr_b16 v[168:169], v154 offset:0x1000
	ds_read_b64_tr_b16 v[170:171], v154 offset:0x1800
	ds_read_b64_tr_b16 v[200:201], v154 offset:0x2000
	ds_read_b64_tr_b16 v[202:203], v154 offset:0x2800
	ds_read_b64_tr_b16 v[204:205], v154 offset:0x3000
	ds_read_b64_tr_b16 v[206:207], v154 offset:0x3800
	s_waitcnt lgkmcnt(6)
; #define SBAR() __builtin_amdgcn_sched_barrier(0)
; __device__ __forceinline__ void partialSM(f32x16& p0, f32x16& p1, float& m_reg, float& mn, float& alpha, float C, float thr) {
;   float pmax = p0[0]; for (int r = 1; r < 16; ++r) pmax = fmaxf(pmax, p0[r]); for (int r = 0; r < 16; ++r) pmax = fmaxf(pmax, p1[r]);
;   { auto rr = __builtin_amdgcn_permlane32_swap(__float_as_uint(pmax), __float_as_uint(pmax), false, false);
;     pmax = fmaxf(__uint_as_float(rr[0]), __uint_as_float(rr[1])); }
;   if (__builtin_expect(__all(pmax - m_reg <= thr), 1)) { mn = m_reg; alpha = 1.f; }
; template <int D0> __device__ __forceinline__ void pv_one(f32x16& od, int vb, bf16x8 pa0, bf16x8 pa1, bf16x8 pa2, bf16x8 pa3) {
;   const s16x4 l0 = tr_read<v_rd_off(D0, 0, 0)>(vb), h0 = tr_read<v_rd_off(D0, 0, 1)>(vb), l1 = tr_read<v_rd_off(D0, 1, 0)>(vb), h1 = tr_read<v_rd_off(D0, 1, 1)>(vb);
;   const s16x4 l2 = tr_read<v_rd_off(D0, 2, 0)>(vb), h2 = tr_read<v_rd_off(D0, 2, 1)>(vb), l3 = tr_read<v_rd_off(D0, 3, 0)>(vb), h3 = tr_read<v_rd_off(D0, 3, 1)>(vb);
;   asm volatile("s_waitcnt lgkmcnt(0)" ::: "memory"); SBAR();
;     ...
;   od = __builtin_amdgcn_mfma_f32_32x32x16_bf16(pa0, PK(l0, h0), od, 0, 0, 0);
;   od = __builtin_amdgcn_mfma_f32_32x32x16_bf16(pa1, PK(l1, h1), od, 0, 0, 0);
;   od = __builtin_amdgcn_mfma_f32_32x32x16_bf16(pa2, PK(l2, h2), od, 0, 0, 0);
;   od = __builtin_amdgcn_mfma_f32_32x32x16_bf16(pa3, PK(l3, h3), od, 0, 0, 0);
;     ...
; }
; __device__ __forceinline__ void pv_d0(f32x16* o, int vb, bf16x8 pa0, bf16x8 pa1, bf16x8 pa2, bf16x8 pa3) {
;   pv_one<0>(o[0], vb, pa0, pa1, pa2, pa3); pv_one<1>(o[1], vb, pa0, pa1, pa2, pa3); pv_one<2>(o[2], vb, pa0, pa1, pa2, pa3); pv_one<3>(o[3], vb, pa0, pa1, pa2, pa3);
	s_nop 0
	v_mfma_f32_32x32x16_bf16 v[0:15], v[136:139], v[164:167], v[0:15]
	ds_read_b64_tr_b16 v[164:165], v154 offset:0x200
	ds_read_b64_tr_b16 v[166:167], v154 offset:0xa00
	s_waitcnt lgkmcnt(6)
	v_mfma_f32_32x32x16_bf16 v[0:15], v[140:143], v[168:171], v[0:15]
	ds_read_b64_tr_b16 v[168:169], v154 offset:0x1200
	ds_read_b64_tr_b16 v[170:171], v154 offset:0x1a00
	s_waitcnt lgkmcnt(6)
	v_mfma_f32_32x32x16_bf16 v[0:15], v[150:153], v[200:203], v[0:15]
	ds_read_b64_tr_b16 v[200:201], v154 offset:0x2200
	ds_read_b64_tr_b16 v[202:203], v154 offset:0x2a00
	s_waitcnt lgkmcnt(6)
	v_mfma_f32_32x32x16_bf16 v[0:15], v[160:163], v[204:207], v[0:15]
	ds_read_b64_tr_b16 v[204:205], v154 offset:0x3200
	ds_read_b64_tr_b16 v[206:207], v154 offset:0x3a00
	s_waitcnt lgkmcnt(6)
	v_mfma_f32_32x32x16_bf16 v[48:63], v[136:139], v[164:167], v[48:63]
	ds_read_b64_tr_b16 v[164:165], v154 offset:0x400
	ds_read_b64_tr_b16 v[166:167], v154 offset:0xc00
	s_waitcnt lgkmcnt(6)
	v_mfma_f32_32x32x16_bf16 v[48:63], v[140:143], v[168:171], v[48:63]
	ds_read_b64_tr_b16 v[168:169], v154 offset:0x1400
	ds_read_b64_tr_b16 v[170:171], v154 offset:0x1c00
	s_waitcnt lgkmcnt(6)
	v_mfma_f32_32x32x16_bf16 v[48:63], v[150:153], v[200:203], v[48:63]
	ds_read_b64_tr_b16 v[200:201], v154 offset:0x2400
	ds_read_b64_tr_b16 v[202:203], v154 offset:0x2c00
	s_waitcnt lgkmcnt(6)
	v_mfma_f32_32x32x16_bf16 v[48:63], v[160:163], v[204:207], v[48:63]
	ds_read_b64_tr_b16 v[204:205], v154 offset:0x3400
	ds_read_b64_tr_b16 v[206:207], v154 offset:0x3c00
	s_waitcnt lgkmcnt(6)
	v_mfma_f32_32x32x16_bf16 v[32:47], v[136:139], v[164:167], v[32:47]
	ds_read_b64_tr_b16 v[164:165], v154 offset:0x600
	ds_read_b64_tr_b16 v[166:167], v154 offset:0xe00
	s_waitcnt lgkmcnt(6)
	v_mfma_f32_32x32x16_bf16 v[32:47], v[140:143], v[168:171], v[32:47]
	ds_read_b64_tr_b16 v[168:169], v154 offset:0x1600
	ds_read_b64_tr_b16 v[170:171], v154 offset:0x1e00
	s_waitcnt lgkmcnt(6)
	v_mfma_f32_32x32x16_bf16 v[32:47], v[150:153], v[200:203], v[32:47]
	ds_read_b64_tr_b16 v[200:201], v154 offset:0x2600
	ds_read_b64_tr_b16 v[202:203], v154 offset:0x2e00
	s_waitcnt lgkmcnt(6)
	v_mfma_f32_32x32x16_bf16 v[32:47], v[160:163], v[204:207], v[32:47]
	ds_read_b64_tr_b16 v[204:205], v154 offset:0x3600
	ds_read_b64_tr_b16 v[206:207], v154 offset:0x3e00
	s_waitcnt lgkmcnt(6)
	v_mfma_f32_32x32x16_bf16 v[16:31], v[136:139], v[164:167], v[16:31]
	v_max_f32_e32 v136, v81, v81
	v_max_f32_e32 v137, v80, v80
	v_max_f32_e32 v136, v137, v136
	v_max3_f32 v136, v136, v82, v83
	v_max3_f32 v136, v136, v84, v85
	v_max3_f32 v136, v136, v86, v87
	v_max3_f32 v136, v136, v88, v89
	s_waitcnt lgkmcnt(4)
	v_mfma_f32_32x32x16_bf16 v[16:31], v[140:143], v[168:171], v[16:31]
	v_max3_f32 v136, v136, v90, v91
	v_max3_f32 v136, v136, v92, v93
	v_max3_f32 v136, v136, v94, v95
	v_max3_f32 v136, v136, v64, v65
	v_max3_f32 v136, v136, v66, v67
	v_max3_f32 v136, v136, v68, v69
	v_max3_f32 v136, v136, v70, v71
	s_waitcnt lgkmcnt(2)
	v_mfma_f32_32x32x16_bf16 v[16:31], v[150:153], v[200:203], v[16:31]
	v_max3_f32 v136, v136, v72, v73
	v_max3_f32 v136, v136, v74, v75
	v_max3_f32 v136, v136, v76, v77
	v_max3_f32 v136, v136, v78, v79
	v_mov_b32_e32 v137, v136
	s_nop 1
	v_permlane32_swap_b32_e32 v136, v137
	s_waitcnt lgkmcnt(0)
	v_mfma_f32_32x32x16_bf16 v[16:31], v[160:163], v[204:207], v[16:31]
	v_max_f32_e32 v137, v137, v137
	v_max_f32_e32 v136, v136, v136
	v_max_f32_e32 v136, v136, v137
	v_sub_f32_e32 v137, v136, v157
	v_cmp_ge_f32_e64 s[8:9], s26, v137
	s_mov_b64 s[18:19], -1
	s_and_b64 vcc, exec, s[16:17]
	s_cbranch_vccz .LBB0_165
	s_waitcnt vmcnt(0)
	s_mov_b64 s[18:19], 0

; __device__ __forceinline__ void partialSM(f32x16& p0, f32x16& p1, float& m_reg, float& mn, float& alpha, float C, float thr) {
;     ...
;   else { mn = fmaxf(m_reg, pmax); alpha = __builtin_amdgcn_exp2f((m_reg - mn) * C); m_reg = mn; }
;   float mnC = -mn * C;
;   for (int r = 0; r < 16; ++r) p0[r] = fmaf(p0[r], C, mnC); for (int r = 0; r < 16; ++r) p1[r] = fmaf(p1[r], C, mnC);
;   for (int r = 0; r < 16; ++r) p0[r] = __builtin_amdgcn_exp2f(p0[r]);
; __device__ __forceinline__ void finishSM(f32x16& p0, f32x16& p1, float alpha, float& l_reg, bf16x8& pa0, bf16x8& pa1, bf16x8& pa2, bf16x8& pa3) {
;   for (int r = 0; r < 16; ++r) p1[r] = __builtin_amdgcn_exp2f(p1[r]);
;   float ps = 0; for (int r = 0; r < 16; ++r) ps += p0[r]; for (int r = 0; r < 16; ++r) ps += p1[r];
;   { auto rr = __builtin_amdgcn_permlane32_swap(__float_as_uint(ps), __float_as_uint(ps), false, false);
;     ps = __uint_as_float(rr[0]) + __uint_as_float(rr[1]); }
;   l_reg = l_reg * alpha + ps;
;     ...
;   PK4(p0, 0, pa0); PK4(p0, 8, pa1); PK4(p1, 0, pa2); PK4(p1, 8, pa3);
; template <int qh> __device__ __forceinline__ void qkt(f32x16& p0, f32x16& p1, const bf16_t* Ks, const bf16x8* qr, int r32, int hi) {
;   p0 = f32x16{}; p1 = f32x16{};
;   if constexpr (qh != 2) { QKT_STEP(0); QKT_STEP(1); QKT_STEP(2); QKT_STEP(3); }
;   if constexpr (qh != 1) { QKT_STEP(4); QKT_STEP(5); QKT_STEP(6); QKT_STEP(7); }
; }
.LBB0_173:
	v_cndmask_b32_e64 v121, v137, v157, s[8:9]
	v_mul_f32_e32 v120, 0xbfb8aa3b, v121
	v_fmamk_f32 v80, v80, 0x3fb8aa3b, v120
	v_fmamk_f32 v81, v81, 0x3fb8aa3b, v120
	v_fmamk_f32 v82, v82, 0x3fb8aa3b, v120
	v_fmamk_f32 v83, v83, 0x3fb8aa3b, v120
	v_fmamk_f32 v84, v84, 0x3fb8aa3b, v120
	v_fmamk_f32 v85, v85, 0x3fb8aa3b, v120
	v_fmamk_f32 v86, v86, 0x3fb8aa3b, v120
	v_fmamk_f32 v87, v87, 0x3fb8aa3b, v120
	v_fmamk_f32 v88, v88, 0x3fb8aa3b, v120
	v_fmamk_f32 v89, v89, 0x3fb8aa3b, v120
	v_fmamk_f32 v90, v90, 0x3fb8aa3b, v120
	v_fmamk_f32 v91, v91, 0x3fb8aa3b, v120
	v_fmamk_f32 v92, v92, 0x3fb8aa3b, v120
	v_fmamk_f32 v93, v93, 0x3fb8aa3b, v120
	v_fmamk_f32 v94, v94, 0x3fb8aa3b, v120
	v_fmamk_f32 v95, v95, 0x3fb8aa3b, v120
	v_fmamk_f32 v126, v64, 0x3fb8aa3b, v120
	v_fmamk_f32 v127, v65, 0x3fb8aa3b, v120
	v_fmamk_f32 v137, v66, 0x3fb8aa3b, v120
	v_fmamk_f32 v142, v67, 0x3fb8aa3b, v120
	v_fmamk_f32 v143, v68, 0x3fb8aa3b, v120
	v_fmamk_f32 v150, v69, 0x3fb8aa3b, v120
	v_fmamk_f32 v151, v70, 0x3fb8aa3b, v120
	v_fmamk_f32 v152, v71, 0x3fb8aa3b, v120
	v_fmamk_f32 v153, v72, 0x3fb8aa3b, v120
	v_fmamk_f32 v154, v73, 0x3fb8aa3b, v120
	v_fmamk_f32 v155, v74, 0x3fb8aa3b, v120
	v_fmamk_f32 v157, v75, 0x3fb8aa3b, v120
	v_fmamk_f32 v159, v76, 0x3fb8aa3b, v120
	v_fmamk_f32 v200, v77, 0x3fb8aa3b, v120
	v_fmamk_f32 v201, v78, 0x3fb8aa3b, v120
	v_fmac_f32_e32 v120, 0x3fb8aa3b, v79
	v_exp_f32_e32 v160, v80
	v_exp_f32_e32 v161, v81
	v_exp_f32_e32 v162, v82
	v_exp_f32_e32 v163, v83
	v_exp_f32_e32 v164, v84
	v_exp_f32_e32 v165, v85
	v_exp_f32_e32 v166, v86
	v_exp_f32_e32 v167, v87
	v_exp_f32_e32 v168, v88
	v_exp_f32_e32 v169, v89
	v_exp_f32_e32 v170, v90
	v_exp_f32_e32 v171, v91
	v_exp_f32_e32 v184, v92
	v_exp_f32_e32 v185, v93
	v_exp_f32_e32 v198, v94
	v_exp_f32_e32 v199, v95
	s_and_b32 s8, s23, 0x18000
	s_add_i32 s8, s8, 0
	v_add_u32_e32 v68, s8, v175
	ds_read_b128 v[64:67], v68
	ds_read_b128 v[68:71], v68 offset:8192
	v_add_u32_e32 v138, s8, v176
	ds_read_b128 v[122:125], v138
	ds_read_b128 v[138:141], v138 offset:8192
	v_exp_f32_e32 v202, v126
	s_waitcnt lgkmcnt(0)
	v_mfma_f32_32x32x16_bf16 v[80:95], v[64:67], v[108:111], 0
	v_exp_f32_e32 v203, v127
	v_exp_f32_e32 v137, v137
	v_exp_f32_e32 v142, v142
	v_exp_f32_e32 v143, v143
	v_exp_f32_e32 v204, v150
	v_exp_f32_e32 v205, v151
	v_exp_f32_e32 v206, v152
	v_mfma_f32_32x32x16_bf16 v[64:79], v[68:71], v[108:111], 0
	v_exp_f32_e32 v207, v153
	v_exp_f32_e32 v154, v154
	v_exp_f32_e32 v155, v155
	v_exp_f32_e32 v157, v157
	v_exp_f32_e32 v159, v159
	v_exp_f32_e32 v200, v200
	v_exp_f32_e32 v201, v201
	v_mfma_f32_32x32x16_bf16 v[80:95], v[122:125], v[104:107], v[80:95]
	v_exp_f32_e32 v120, v120
	v_cvt_pk_bf16_f32 v126, v164, v165
	v_cvt_pk_bf16_f32 v127, v166, v167
	v_cvt_pk_bf16_f32 v150, v202, v203
	v_cvt_pk_bf16_f32 v151, v137, v142
	v_cvt_pk_bf16_f32 v152, v143, v204
	v_cvt_pk_bf16_f32 v153, v205, v206
	v_mfma_f32_32x32x16_bf16 v[64:79], v[138:141], v[104:107], v[64:79]
	v_add_u32_e32 v138, s8, v177
	ds_read_b128 v[122:125], v138
	ds_read_b128 v[138:141], v138 offset:8192
	v_add_u32_e32 v236, s8, v178
	ds_read_b128 v[228:231], v236
	ds_read_b128 v[232:235], v236 offset:8192
	v_permlane32_swap_b32_e32 v150, v152
	v_permlane32_swap_b32_e32 v151, v153
	s_waitcnt lgkmcnt(2)
	v_mfma_f32_32x32x16_bf16 v[80:95], v[122:125], v[100:103], v[80:95]
	v_mfma_f32_32x32x16_bf16 v[64:79], v[138:141], v[100:103], v[64:79]
	s_waitcnt lgkmcnt(0)
	v_mfma_f32_32x32x16_bf16 v[80:95], v[228:231], v[96:99], v[80:95]
	v_add_f32_e32 v122, 0, v160
	v_add_f32_e32 v122, v161, v122
	v_add_f32_e32 v122, v162, v122
	v_add_f32_e32 v122, v163, v122
	v_add_f32_e32 v122, v164, v122
	v_add_f32_e32 v122, v165, v122
	v_add_f32_e32 v122, v166, v122
	v_add_f32_e32 v122, v167, v122
	v_add_f32_e32 v122, v168, v122
	v_add_f32_e32 v122, v169, v122
	v_add_f32_e32 v122, v170, v122
	v_add_f32_e32 v122, v171, v122
	v_add_f32_e32 v122, v184, v122
	v_add_f32_e32 v122, v185, v122
	v_add_f32_e32 v122, v198, v122
	v_add_f32_e32 v122, v199, v122
	v_add_f32_e32 v122, v202, v122
	v_add_f32_e32 v122, v203, v122
	v_add_f32_e32 v122, v137, v122
	v_add_f32_e32 v122, v142, v122
	v_add_f32_e32 v122, v143, v122
	v_add_f32_e32 v122, v204, v122
	v_add_f32_e32 v122, v205, v122
	v_add_f32_e32 v122, v206, v122
	v_add_f32_e32 v122, v207, v122
	v_add_f32_e32 v122, v154, v122
	v_mfma_f32_32x32x16_bf16 v[64:79], v[232:235], v[96:99], v[64:79]
	v_add_f32_e32 v122, v155, v122
	v_add_f32_e32 v122, v157, v122
	v_add_f32_e32 v122, v159, v122
	v_add_f32_e32 v122, v200, v122
	v_add_f32_e32 v122, v201, v122
	v_add_f32_e32 v122, v120, v122
	v_mov_b32_e32 v123, v122
	s_nop 1
	v_permlane32_swap_b32_e32 v122, v123
	v_cvt_pk_bf16_f32 v124, v160, v161
	v_cvt_pk_bf16_f32 v125, v162, v163
	v_cvt_pk_bf16_f32 v138, v168, v169
	v_cvt_pk_bf16_f32 v139, v170, v171
	v_cvt_pk_bf16_f32 v140, v184, v185
	v_cvt_pk_bf16_f32 v141, v198, v199
	v_cvt_pk_bf16_f32 v160, v207, v154
	v_cvt_pk_bf16_f32 v161, v155, v157
	v_cvt_pk_bf16_f32 v162, v159, v200
	v_cvt_pk_bf16_f32 v163, v201, v120
	v_permlane32_swap_b32_e32 v124, v126
	v_permlane32_swap_b32_e32 v125, v127
	v_permlane32_swap_b32_e32 v138, v140
	v_permlane32_swap_b32_e32 v139, v141
	v_permlane32_swap_b32_e32 v160, v162
	v_permlane32_swap_b32_e32 v161, v163
	v_add_u32_e32 v120, s24, v173
	ds_read_b64_tr_b16 v[164:165], v120 offset:0
	ds_read_b64_tr_b16 v[166:167], v120 offset:0x800
	ds_read_b64_tr_b16 v[168:169], v120 offset:0x1000
	ds_read_b64_tr_b16 v[170:171], v120 offset:0x1800
	ds_read_b64_tr_b16 v[200:201], v120 offset:0x2000
	ds_read_b64_tr_b16 v[202:203], v120 offset:0x2800
	ds_read_b64_tr_b16 v[204:205], v120 offset:0x3000
	ds_read_b64_tr_b16 v[206:207], v120 offset:0x3800
	s_waitcnt lgkmcnt(6)
; #define SBAR() __builtin_amdgcn_sched_barrier(0)
; __device__ __forceinline__ void partialSM(f32x16& p0, f32x16& p1, float& m_reg, float& mn, float& alpha, float C, float thr) {
;   float pmax = p0[0]; for (int r = 1; r < 16; ++r) pmax = fmaxf(pmax, p0[r]); for (int r = 0; r < 16; ++r) pmax = fmaxf(pmax, p1[r]);
;   { auto rr = __builtin_amdgcn_permlane32_swap(__float_as_uint(pmax), __float_as_uint(pmax), false, false);
;     pmax = fmaxf(__uint_as_float(rr[0]), __uint_as_float(rr[1])); }
;   if (__builtin_expect(__all(pmax - m_reg <= thr), 1)) { mn = m_reg; alpha = 1.f; }
; template <int D0> __device__ __forceinline__ void pv_one(f32x16& od, int vb, bf16x8 pa0, bf16x8 pa1, bf16x8 pa2, bf16x8 pa3) {
;   const s16x4 l0 = tr_read<v_rd_off(D0, 0, 0)>(vb), h0 = tr_read<v_rd_off(D0, 0, 1)>(vb), l1 = tr_read<v_rd_off(D0, 1, 0)>(vb), h1 = tr_read<v_rd_off(D0, 1, 1)>(vb);
;   const s16x4 l2 = tr_read<v_rd_off(D0, 2, 0)>(vb), h2 = tr_read<v_rd_off(D0, 2, 1)>(vb), l3 = tr_read<v_rd_off(D0, 3, 0)>(vb), h3 = tr_read<v_rd_off(D0, 3, 1)>(vb);
;   asm volatile("s_waitcnt lgkmcnt(0)" ::: "memory"); SBAR();
;     ...
;   od = __builtin_amdgcn_mfma_f32_32x32x16_bf16(pa0, PK(l0, h0), od, 0, 0, 0);
;   od = __builtin_amdgcn_mfma_f32_32x32x16_bf16(pa1, PK(l1, h1), od, 0, 0, 0);
;   od = __builtin_amdgcn_mfma_f32_32x32x16_bf16(pa2, PK(l2, h2), od, 0, 0, 0);
;   od = __builtin_amdgcn_mfma_f32_32x32x16_bf16(pa3, PK(l3, h3), od, 0, 0, 0);
;     ...
; }
; __device__ __forceinline__ void pv_d0(f32x16* o, int vb, bf16x8 pa0, bf16x8 pa1, bf16x8 pa2, bf16x8 pa3) {
;   pv_one<0>(o[0], vb, pa0, pa1, pa2, pa3); pv_one<1>(o[1], vb, pa0, pa1, pa2, pa3); pv_one<2>(o[2], vb, pa0, pa1, pa2, pa3); pv_one<3>(o[3], vb, pa0, pa1, pa2, pa3);
	s_nop 0
	v_mfma_f32_32x32x16_bf16 v[0:15], v[124:127], v[164:167], v[0:15]
	ds_read_b64_tr_b16 v[164:165], v120 offset:0x200
	ds_read_b64_tr_b16 v[166:167], v120 offset:0xa00
	s_waitcnt lgkmcnt(6)
	v_mfma_f32_32x32x16_bf16 v[0:15], v[138:141], v[168:171], v[0:15]
	ds_read_b64_tr_b16 v[168:169], v120 offset:0x1200
	ds_read_b64_tr_b16 v[170:171], v120 offset:0x1a00
	s_waitcnt lgkmcnt(6)
	v_mfma_f32_32x32x16_bf16 v[0:15], v[150:153], v[200:203], v[0:15]
	ds_read_b64_tr_b16 v[200:201], v120 offset:0x2200
	ds_read_b64_tr_b16 v[202:203], v120 offset:0x2a00
	s_waitcnt lgkmcnt(6)
	v_mfma_f32_32x32x16_bf16 v[0:15], v[160:163], v[204:207], v[0:15]
	ds_read_b64_tr_b16 v[204:205], v120 offset:0x3200
	ds_read_b64_tr_b16 v[206:207], v120 offset:0x3a00
	s_waitcnt lgkmcnt(6)
	v_mfma_f32_32x32x16_bf16 v[48:63], v[124:127], v[164:167], v[48:63]
	ds_read_b64_tr_b16 v[164:165], v120 offset:0x400
	ds_read_b64_tr_b16 v[166:167], v120 offset:0xc00
	s_waitcnt lgkmcnt(6)
	v_mfma_f32_32x32x16_bf16 v[48:63], v[138:141], v[168:171], v[48:63]
	ds_read_b64_tr_b16 v[168:169], v120 offset:0x1400
	ds_read_b64_tr_b16 v[170:171], v120 offset:0x1c00
	s_waitcnt lgkmcnt(6)
	v_mfma_f32_32x32x16_bf16 v[48:63], v[150:153], v[200:203], v[48:63]
	ds_read_b64_tr_b16 v[200:201], v120 offset:0x2400
	ds_read_b64_tr_b16 v[202:203], v120 offset:0x2c00
	s_waitcnt lgkmcnt(6)
	v_mfma_f32_32x32x16_bf16 v[48:63], v[160:163], v[204:207], v[48:63]
	ds_read_b64_tr_b16 v[204:205], v120 offset:0x3400
	ds_read_b64_tr_b16 v[206:207], v120 offset:0x3c00
	s_waitcnt lgkmcnt(6)
	v_mfma_f32_32x32x16_bf16 v[32:47], v[124:127], v[164:167], v[32:47]
	ds_read_b64_tr_b16 v[164:165], v120 offset:0x600
	ds_read_b64_tr_b16 v[166:167], v120 offset:0xe00
	s_waitcnt lgkmcnt(6)
	v_mfma_f32_32x32x16_bf16 v[32:47], v[138:141], v[168:171], v[32:47]
	ds_read_b64_tr_b16 v[168:169], v120 offset:0x1600
	ds_read_b64_tr_b16 v[170:171], v120 offset:0x1e00
	s_waitcnt lgkmcnt(6)
	v_mfma_f32_32x32x16_bf16 v[32:47], v[150:153], v[200:203], v[32:47]
	ds_read_b64_tr_b16 v[200:201], v120 offset:0x2600
	ds_read_b64_tr_b16 v[202:203], v120 offset:0x2e00
	s_waitcnt lgkmcnt(6)
	v_mfma_f32_32x32x16_bf16 v[32:47], v[160:163], v[204:207], v[32:47]
	ds_read_b64_tr_b16 v[204:205], v120 offset:0x3600
	ds_read_b64_tr_b16 v[206:207], v120 offset:0x3e00
	s_waitcnt lgkmcnt(6)
	v_mfma_f32_32x32x16_bf16 v[16:31], v[124:127], v[164:167], v[16:31]
	v_max_f32_e32 v120, v81, v81
	v_max_f32_e32 v124, v80, v80
	v_max_f32_e32 v120, v124, v120
	v_max3_f32 v120, v120, v82, v83
	v_max3_f32 v120, v120, v84, v85
	v_max3_f32 v120, v120, v86, v87
	v_max3_f32 v120, v120, v88, v89
	s_waitcnt lgkmcnt(4)
	v_mfma_f32_32x32x16_bf16 v[16:31], v[138:141], v[168:171], v[16:31]
	v_max3_f32 v120, v120, v90, v91
	v_max3_f32 v120, v120, v92, v93
	v_max3_f32 v120, v120, v94, v95
	v_max3_f32 v120, v120, v64, v65
	v_max3_f32 v120, v120, v66, v67
	v_max3_f32 v120, v120, v68, v69
	v_max3_f32 v120, v120, v70, v71
	s_waitcnt lgkmcnt(2)
	v_mfma_f32_32x32x16_bf16 v[16:31], v[150:153], v[200:203], v[16:31]
	v_max3_f32 v120, v120, v72, v73
	v_max3_f32 v120, v120, v74, v75
	v_max3_f32 v120, v120, v76, v77
	v_max3_f32 v120, v120, v78, v79
	v_mov_b32_e32 v124, v120
	s_nop 1
	v_permlane32_swap_b32_e32 v120, v124
	s_waitcnt lgkmcnt(0)
	v_mfma_f32_32x32x16_bf16 v[16:31], v[160:163], v[204:207], v[16:31]
	v_max_f32_e32 v124, v124, v124
	v_max_f32_e32 v120, v120, v120
	v_max_f32_e32 v120, v120, v124
	v_sub_f32_e32 v124, v120, v121
	v_cmp_ge_f32_e64 s[8:9], s26, v124
	s_mov_b64 s[18:19], -1
	s_and_b64 vcc, exec, s[16:17]
	s_cbranch_vccz .LBB0_175
	s_waitcnt vmcnt(0)
	s_mov_b64 s[18:19], 0
